# EpiUp: drop dead zero-inits before full-row DPP rotates; HG3 carry-in: prefetch gains+state fragments one k-step ahead
# speedup vs baseline: 1.0049x; 1.0049x over previous
; DI f32x4 mfma32(bf16x8 a, bf16x8 b, f32x4 c) { return __builtin_amdgcn_mfma_f32_16x16x32_bf16(a, b, c, 0, 0, 0); }
; DI void phase_hg3(const Ctx& c, LAS unsigned char* lds, int g, int l, const bf16* PROJ, const bf16* ST, const bf16* RT, const float* GC, const bf16* KT1, const bf16* QTB, bf16* MIX, int bid, int nb, int tid) {
;     ...
; #pragma unroll
;             for (int ks = 0; ks < 4; ++ks) {
;                 if (ks < 3) {
; #pragma unroll
;                     for (int vt = 0; vt < 8; ++vt) sa[(ks + 1) & 1][vt] = *(const bf16x8*)(ST + su * 16384 + ((vt * 4 + ks + 1) * 64 + lane) * 8); }
; #pragma unroll
;                 for (int vt = 0; vt < 8; ++vt) o[vt] = mfma32(sa[ks & 1][vt], qt[ks], o[vt]);
;             }
;             { const int sq_ = cgk / ncs, cs = cgk - sq_ * ncs, p = dir ? ncs - 1 - cs : cs, blk = p >> 3;
;               if (blk > 0) { const size_t rr = (size_t)((sq_ * 8 + h * 2 + dir) * rps + blk);
.LBB0_400:
	s_or_b64 exec, exec, vcc
	v_add_co_u32_e32 v90, vcc, s97, v136
	s_waitcnt vmcnt(5)
	v_mfma_f32_16x16x32_bf16 v[42:45], v[42:45], v[18:21], v[66:69]
	v_addc_co_u32_e32 v91, vcc, 0, v137, vcc
	s_movk_i32 s96, 0x3000
	s_nop 0
	global_load_dwordx4 v[66:69], v[136:137], off offset:1024
	s_waitcnt vmcnt(3)
	v_mfma_f32_16x16x32_bf16 v[26:29], v[26:29], v[18:21], v[62:65]
	s_movk_i32 s34, 0x4000
	s_movk_i32 s60, 0x5000
	s_movk_i32 s59, 0x6000
	global_load_dwordx4 v[62:65], v[90:91], off offset:1024
	v_mfma_f32_16x16x32_bf16 v[38:41], v[38:41], v[18:21], v[78:81]
	s_movk_i32 s61, 0x7000
	s_abs_i32 s18, s0
	v_readlane_b32 s19, v254, 52
	v_add_co_u32_e32 v78, vcc, s1, v136
	s_waitcnt vmcnt(2)
	v_mfma_f32_16x16x32_bf16 v[22:25], v[22:25], v[18:21], v[54:57]
	v_addc_co_u32_e32 v79, vcc, 0, v137, vcc
	v_add_co_u32_e32 v92, vcc, s96, v136
	s_nop 0
	global_load_dwordx4 v[54:57], v[78:79], off offset:1024
	v_mfma_f32_16x16x32_bf16 v[50:53], v[50:53], v[18:21], v[82:85]
	v_addc_co_u32_e32 v93, vcc, 0, v137, vcc
	s_mul_hi_u32 s19, s18, s19
	v_mfma_f32_16x16x32_bf16 v[46:49], v[46:49], v[18:21], v[74:77]
	v_add_co_u32_e32 v82, vcc, s34, v136
	v_readlane_b32 s33, v254, 53
	v_mfma_f32_16x16x32_bf16 v[34:37], v[34:37], v[18:21], v[70:73]
	v_addc_co_u32_e32 v83, vcc, 0, v137, vcc
	v_add_co_u32_e32 v94, vcc, s60, v136
	v_mfma_f32_16x16x32_bf16 v[30:33], v[30:33], v[18:21], v[58:61]
	s_nop 2
	global_load_dwordx4 v[58:61], v[136:137], off offset:2048
	global_load_dwordx4 v[70:73], v[92:93], off offset:1024
	v_addc_co_u32_e32 v95, vcc, 0, v137, vcc
	v_add_co_u32_e32 v86, vcc, s59, v136
	s_mul_i32 s26, s19, s33
	s_nop 0
	v_addc_co_u32_e32 v87, vcc, 0, v137, vcc
	v_add_co_u32_e32 v98, vcc, s61, v136
	s_sub_i32 s18, s18, s26
	s_nop 0
	v_addc_co_u32_e32 v99, vcc, 0, v137, vcc
	s_ashr_i32 s1, s0, 31
	s_add_i32 s26, s19, 1
	s_sub_i32 s27, s18, s33
	s_cmp_ge_u32 s18, s33
	s_cselect_b32 s19, s26, s19
	s_cselect_b32 s18, s27, s18
	s_add_i32 s26, s19, 1
	s_cmp_ge_u32 s18, s33
	s_cselect_b32 s18, s26, s19
	s_xor_b32 s18, s18, s1
	s_sub_i32 s1, s18, s1
	v_readlane_b32 s18, v254, 38
	s_lshl_b32 s18, s1, s18
	s_sub_i32 s33, s0, s18
	s_ashr_i32 s0, s33, 3
	s_movk_i32 s35, 0x2000
	s_cmp_lt_i32 s0, 1
	s_waitcnt vmcnt(4)
	v_mfma_f32_16x16x32_bf16 v[50:53], v[66:69], v[14:17], v[50:53]
	global_load_dwordx4 v[66:69], v[136:137], off offset:3072
	s_waitcnt vmcnt(4)
	v_mfma_f32_16x16x32_bf16 v[46:49], v[62:65], v[14:17], v[46:49]
	global_load_dwordx4 v[62:65], v[82:83], off offset:1024
	global_load_dwordx4 v[74:77], v[78:79], off offset:2048
	s_waitcnt vmcnt(5)
	v_mfma_f32_16x16x32_bf16 v[42:45], v[54:57], v[14:17], v[42:45]
	global_load_dwordx4 v[54:57], v[94:95], off offset:1024
	s_nop 0
	global_load_dwordx4 v[78:81], v[78:79], off offset:3072
	s_waitcnt vmcnt(5)
	v_mfma_f32_16x16x32_bf16 v[34:37], v[70:73], v[14:17], v[34:37]
	global_load_dwordx4 v[70:73], v[82:83], off offset:2048
	v_mfma_f32_16x16x32_bf16 v[50:53], v[58:61], v[10:13], v[50:53]
	s_waitcnt vmcnt(4)
	v_mfma_f32_16x16x32_bf16 v[38:41], v[62:65], v[14:17], v[38:41]
	global_load_dwordx4 v[62:65], v[86:87], off offset:1024
	s_nop 0
	global_load_dwordx4 v[82:85], v[82:83], off offset:3072
	s_waitcnt vmcnt(4)
	v_mfma_f32_16x16x32_bf16 v[26:29], v[54:57], v[14:17], v[26:29]
	global_load_dwordx4 v[54:57], v[86:87], off offset:2048
	v_mfma_f32_16x16x32_bf16 v[42:45], v[74:77], v[10:13], v[42:45]
	s_waitcnt vmcnt(3)
	v_mfma_f32_16x16x32_bf16 v[38:41], v[70:73], v[10:13], v[38:41]
	v_mfma_f32_16x16x32_bf16 v[66:69], v[66:69], v[6:9], v[50:53]
	v_mfma_f32_16x16x32_bf16 v[74:77], v[78:81], v[6:9], v[42:45]
	s_waitcnt vmcnt(2)
	v_mfma_f32_16x16x32_bf16 v[30:33], v[62:65], v[14:17], v[30:33]
	global_load_dwordx4 v[62:65], v[98:99], off offset:1024
	s_nop 0
	global_load_dwordx4 v[86:89], v[86:87], off offset:3072
	s_waitcnt vmcnt(2)
	v_mfma_f32_16x16x32_bf16 v[30:33], v[54:57], v[10:13], v[30:33]
	v_mfma_f32_16x16x32_bf16 v[54:57], v[82:85], v[6:9], v[38:41]
	s_waitcnt vmcnt(1)
	v_mfma_f32_16x16x32_bf16 v[22:25], v[62:65], v[14:17], v[22:25]
	global_load_dwordx4 v[58:61], v[90:91], off offset:2048
	global_load_dwordx4 v[62:65], v[90:91], off offset:3072
	s_waitcnt vmcnt(1)
	v_mfma_f32_16x16x32_bf16 v[46:49], v[58:61], v[10:13], v[46:49]
	global_load_dwordx4 v[58:61], v[92:93], off offset:2048
	s_nop 0
	global_load_dwordx4 v[90:93], v[92:93], off offset:3072
	s_waitcnt vmcnt(2)
	v_mfma_f32_16x16x32_bf16 v[70:73], v[62:65], v[6:9], v[46:49]
	s_waitcnt vmcnt(1)
	v_mfma_f32_16x16x32_bf16 v[34:37], v[58:61], v[10:13], v[34:37]
	global_load_dwordx4 v[58:61], v[94:95], off offset:2048
	s_nop 0
	global_load_dwordx4 v[94:97], v[94:95], off offset:3072
	s_waitcnt vmcnt(2)
	v_mfma_f32_16x16x32_bf16 v[62:65], v[90:93], v[6:9], v[34:37]
	s_waitcnt vmcnt(1)
	v_mfma_f32_16x16x32_bf16 v[26:29], v[58:61], v[10:13], v[26:29]
	global_load_dwordx4 v[58:61], v[98:99], off offset:2048
	s_nop 0
	global_load_dwordx4 v[98:101], v[98:99], off offset:3072
	s_waitcnt vmcnt(1)
	v_mfma_f32_16x16x32_bf16 v[22:25], v[58:61], v[10:13], v[22:25]
	v_mfma_f32_16x16x32_bf16 v[58:61], v[94:97], v[6:9], v[26:29]
	v_mfma_f32_16x16x32_bf16 v[94:97], v[86:89], v[6:9], v[30:33]
	s_nop 1
	v_lshlrev_b32_e32 v26, 1, v149
	v_lshl_add_u32 v181, s1, 3, v26
	s_waitcnt vmcnt(0)
	v_mfma_f32_16x16x32_bf16 v[90:93], v[98:101], v[6:9], v[22:25]
	s_cbranch_scc1 .LBB0_404
; DI f32x4 mfma32(bf16x8 a, bf16x8 b, f32x4 c) { return __builtin_amdgcn_mfma_f32_16x16x32_bf16(a, b, c, 0, 0, 0); }
; DI void phase_hg3(const Ctx& c, LAS unsigned char* lds, int g, int l, const bf16* PROJ, const bf16* ST, const bf16* RT, const float* GC, const bf16* KT1, const bf16* QTB, bf16* MIX, int bid, int nb, int tid) {
;     ...
;             { const int sq_ = cgk / ncs, cs = cgk - sq_ * ncs, p = dir ? ncs - 1 - cs : cs, blk = p >> 3;
;               if (blk > 0) { const size_t rr = (size_t)((sq_ * 8 + h * 2 + dir) * rps + blk);
; #pragma unroll
;                 for (int ks = 0; ks < 4; ++ks) { const float* gp = GC + su * 128 + ks * 32 + gq * 8; const bf16x8 q2 = scale8(qt[ks], *(const f32x4*)gp, *(const f32x4*)(gp + 4));
; #pragma unroll
;                     for (int vt = 0; vt < 8; ++vt) sa[0][vt] = *(const bf16x8*)(RT + rr * 16384 + ((vt * 4 + ks) * 64 + lane) * 8);
; #pragma unroll
;                     for (int vt = 0; vt < 8; ++vt) o[vt] = mfma32(sa[0][vt], q2, o[vt]); } } }
	v_readlane_b32 s1, v254, 44
	s_nop 0
	v_lshlrev_b64 v[24:25], 10, v[134:135]
	v_lshl_add_u64 v[50:51], v[2:3], 0, v[24:25]
	v_lshlrev_b32_e32 v22, s1, v181
	v_add_u32_e32 v22, s0, v22
	v_ashrrev_i32_e32 v23, 31, v22
	v_lshlrev_b64 v[30:31], 15, v[22:23]
	v_lshl_add_u64 v[52:53], v[146:147], 0, v[30:31]
	s_movk_i32 s18, 0x2000
	s_mov_b64 vcc, 0x1000
	v_lshl_add_u64 v[80:81], vcc, 0, v[52:53]
	s_mov_b64 vcc, 0x3000
	v_lshl_add_u64 v[84:85], vcc, 0, v[52:53]
	s_mov_b64 vcc, 0x5000
	v_lshl_add_u64 v[88:89], vcc, 0, v[52:53]
	s_mov_b64 vcc, 0x7000
	v_lshl_add_u64 v[78:79], vcc, 0, v[52:53]
	global_load_dwordx4 v[22:25], v[50:51], off offset:16
	global_load_dwordx4 v[26:29], v[50:51], off
	global_load_dwordx4 v[30:33], v[50:51], off offset:144
	global_load_dwordx4 v[34:37], v[50:51], off offset:128
	global_load_dwordx4 v[38:41], v[50:51], off offset:272
	global_load_dwordx4 v[42:45], v[50:51], off offset:256
	global_load_dwordx4 v[46:49], v[50:51], off offset:400
	global_load_dwordx4 v[100:103], v[50:51], off offset:384
	global_load_dwordx4 v[104:107], v[80:81], off offset:-4096
	global_load_dwordx4 v[108:111], v[80:81], off
	global_load_dwordx4 v[112:115], v[84:85], off offset:-4096
	global_load_dwordx4 v[116:119], v[84:85], off
	global_load_dwordx4 v[120:123], v[88:89], off offset:-4096
	global_load_dwordx4 v[124:127], v[88:89], off
	global_load_dwordx4 v[128:131], v[78:79], off offset:-4096
	global_load_dwordx4 v[138:141], v[78:79], off
	s_waitcnt vmcnt(8)
	v_lshlrev_b32_e32 v132, 16, v18
	v_and_b32_e32 v133, 0xffff0000, v18
	v_lshlrev_b32_e32 v202, 16, v19
	v_and_b32_e32 v203, 0xffff0000, v19
	v_pk_mul_f32 v[132:133], v[26:27], v[132:133]
	v_pk_mul_f32 v[202:203], v[28:29], v[202:203]
	v_cvt_pk_bf16_f32 v18, v132, v133
	v_cvt_pk_bf16_f32 v19, v202, v203
	v_lshlrev_b32_e32 v132, 16, v20
	v_and_b32_e32 v133, 0xffff0000, v20
	v_lshlrev_b32_e32 v202, 16, v21
	v_and_b32_e32 v203, 0xffff0000, v21
	v_pk_mul_f32 v[132:133], v[22:23], v[132:133]
	v_pk_mul_f32 v[202:203], v[24:25], v[202:203]
	v_cvt_pk_bf16_f32 v20, v132, v133
	v_cvt_pk_bf16_f32 v21, v202, v203
	v_lshlrev_b32_e32 v132, 16, v14
	v_and_b32_e32 v133, 0xffff0000, v14
	v_lshlrev_b32_e32 v202, 16, v15
	v_and_b32_e32 v203, 0xffff0000, v15
	v_pk_mul_f32 v[132:133], v[34:35], v[132:133]
	v_pk_mul_f32 v[202:203], v[36:37], v[202:203]
	v_cvt_pk_bf16_f32 v14, v132, v133
	v_cvt_pk_bf16_f32 v15, v202, v203
	v_lshlrev_b32_e32 v132, 16, v16
	v_and_b32_e32 v133, 0xffff0000, v16
	v_lshlrev_b32_e32 v202, 16, v17
	v_and_b32_e32 v203, 0xffff0000, v17
	v_pk_mul_f32 v[132:133], v[30:31], v[132:133]
	v_pk_mul_f32 v[202:203], v[32:33], v[202:203]
	v_cvt_pk_bf16_f32 v16, v132, v133
	v_cvt_pk_bf16_f32 v17, v202, v203
	v_lshlrev_b32_e32 v132, 16, v10
	v_and_b32_e32 v133, 0xffff0000, v10
	v_lshlrev_b32_e32 v202, 16, v11
	v_and_b32_e32 v203, 0xffff0000, v11
	v_pk_mul_f32 v[132:133], v[42:43], v[132:133]
	v_pk_mul_f32 v[202:203], v[44:45], v[202:203]
	v_cvt_pk_bf16_f32 v10, v132, v133
	v_cvt_pk_bf16_f32 v11, v202, v203
	v_lshlrev_b32_e32 v132, 16, v12
	v_and_b32_e32 v133, 0xffff0000, v12
	v_lshlrev_b32_e32 v202, 16, v13
	v_and_b32_e32 v203, 0xffff0000, v13
	v_pk_mul_f32 v[132:133], v[38:39], v[132:133]
	v_pk_mul_f32 v[202:203], v[40:41], v[202:203]
	v_cvt_pk_bf16_f32 v12, v132, v133
	v_cvt_pk_bf16_f32 v13, v202, v203
	v_lshlrev_b32_e32 v132, 16, v6
	v_and_b32_e32 v133, 0xffff0000, v6
	v_lshlrev_b32_e32 v202, 16, v7
	v_and_b32_e32 v203, 0xffff0000, v7
	v_pk_mul_f32 v[132:133], v[100:101], v[132:133]
	v_pk_mul_f32 v[202:203], v[102:103], v[202:203]
	v_cvt_pk_bf16_f32 v6, v132, v133
	v_cvt_pk_bf16_f32 v7, v202, v203
	v_lshlrev_b32_e32 v132, 16, v8
	v_and_b32_e32 v133, 0xffff0000, v8
	v_lshlrev_b32_e32 v202, 16, v9
	v_and_b32_e32 v203, 0xffff0000, v9
	v_pk_mul_f32 v[132:133], v[46:47], v[132:133]
	v_pk_mul_f32 v[202:203], v[48:49], v[202:203]
	v_cvt_pk_bf16_f32 v8, v132, v133
	v_cvt_pk_bf16_f32 v9, v202, v203
	global_load_dwordx4 v[22:25], v[80:81], off offset:-3072
	global_load_dwordx4 v[26:29], v[80:81], off offset:1024
	global_load_dwordx4 v[30:33], v[84:85], off offset:-3072
	global_load_dwordx4 v[34:37], v[84:85], off offset:1024
	global_load_dwordx4 v[38:41], v[88:89], off offset:-3072
	global_load_dwordx4 v[42:45], v[88:89], off offset:1024
	global_load_dwordx4 v[46:49], v[78:79], off offset:-3072
	global_load_dwordx4 v[100:103], v[78:79], off offset:1024
	s_waitcnt vmcnt(15)
; DI f32x4 mfma32(bf16x8 a, bf16x8 b, f32x4 c) { return __builtin_amdgcn_mfma_f32_16x16x32_bf16(a, b, c, 0, 0, 0); }
; DI void phase_hg3(const Ctx& c, LAS unsigned char* lds, int g, int l, const bf16* PROJ, const bf16* ST, const bf16* RT, const float* GC, const bf16* KT1, const bf16* QTB, bf16* MIX, int bid, int nb, int tid) {
;     ...
;                 for (int ks = 0; ks < 4; ++ks) { const float* gp = GC + su * 128 + ks * 32 + gq * 8; const bf16x8 q2 = scale8(qt[ks], *(const f32x4*)gp, *(const f32x4*)(gp + 4));
; #pragma unroll
;                     for (int vt = 0; vt < 8; ++vt) sa[0][vt] = *(const bf16x8*)(RT + rr * 16384 + ((vt * 4 + ks) * 64 + lane) * 8);
; #pragma unroll
;                     for (int vt = 0; vt < 8; ++vt) o[vt] = mfma32(sa[0][vt], q2, o[vt]); } } }
	v_mfma_f32_16x16x32_bf16 v[66:69], v[104:107], v[18:21], v[66:69]
	s_waitcnt vmcnt(14)
	v_mfma_f32_16x16x32_bf16 v[70:73], v[108:111], v[18:21], v[70:73]
	s_waitcnt vmcnt(13)
	v_mfma_f32_16x16x32_bf16 v[74:77], v[112:115], v[18:21], v[74:77]
	s_waitcnt vmcnt(12)
	v_mfma_f32_16x16x32_bf16 v[62:65], v[116:119], v[18:21], v[62:65]
	s_waitcnt vmcnt(11)
	v_mfma_f32_16x16x32_bf16 v[54:57], v[120:123], v[18:21], v[54:57]
	s_waitcnt vmcnt(10)
	v_mfma_f32_16x16x32_bf16 v[58:61], v[124:127], v[18:21], v[58:61]
	s_waitcnt vmcnt(9)
	v_mfma_f32_16x16x32_bf16 v[94:97], v[128:131], v[18:21], v[94:97]
	s_waitcnt vmcnt(8)
	v_mfma_f32_16x16x32_bf16 v[90:93], v[138:141], v[18:21], v[90:93]
	global_load_dwordx4 v[104:107], v[80:81], off offset:-2048
	global_load_dwordx4 v[108:111], v[80:81], off offset:2048
	global_load_dwordx4 v[112:115], v[84:85], off offset:-2048
	global_load_dwordx4 v[116:119], v[84:85], off offset:2048
	global_load_dwordx4 v[120:123], v[88:89], off offset:-2048
	global_load_dwordx4 v[124:127], v[88:89], off offset:2048
	global_load_dwordx4 v[128:131], v[78:79], off offset:-2048
	global_load_dwordx4 v[138:141], v[78:79], off offset:2048
	s_waitcnt vmcnt(15)
	v_mfma_f32_16x16x32_bf16 v[66:69], v[22:25], v[14:17], v[66:69]
	s_waitcnt vmcnt(14)
	v_mfma_f32_16x16x32_bf16 v[70:73], v[26:29], v[14:17], v[70:73]
	s_waitcnt vmcnt(13)
	v_mfma_f32_16x16x32_bf16 v[74:77], v[30:33], v[14:17], v[74:77]
	s_waitcnt vmcnt(12)
	v_mfma_f32_16x16x32_bf16 v[62:65], v[34:37], v[14:17], v[62:65]
	s_waitcnt vmcnt(11)
	v_mfma_f32_16x16x32_bf16 v[54:57], v[38:41], v[14:17], v[54:57]
	s_waitcnt vmcnt(10)
	v_mfma_f32_16x16x32_bf16 v[58:61], v[42:45], v[14:17], v[58:61]
	s_waitcnt vmcnt(9)
	v_mfma_f32_16x16x32_bf16 v[94:97], v[46:49], v[14:17], v[94:97]
	s_waitcnt vmcnt(8)
	v_mfma_f32_16x16x32_bf16 v[90:93], v[100:103], v[14:17], v[90:93]
	global_load_dwordx4 v[22:25], v[80:81], off offset:-1024
	global_load_dwordx4 v[26:29], v[80:81], off offset:3072
	global_load_dwordx4 v[30:33], v[84:85], off offset:-1024
	global_load_dwordx4 v[34:37], v[84:85], off offset:3072
	global_load_dwordx4 v[38:41], v[88:89], off offset:-1024
	global_load_dwordx4 v[42:45], v[88:89], off offset:3072
	global_load_dwordx4 v[46:49], v[78:79], off offset:-1024
	global_load_dwordx4 v[100:103], v[78:79], off offset:3072
	s_waitcnt vmcnt(15)
	v_mfma_f32_16x16x32_bf16 v[66:69], v[104:107], v[10:13], v[66:69]
	s_waitcnt vmcnt(14)
	v_mfma_f32_16x16x32_bf16 v[70:73], v[108:111], v[10:13], v[70:73]
	s_waitcnt vmcnt(13)
	v_mfma_f32_16x16x32_bf16 v[74:77], v[112:115], v[10:13], v[74:77]
	s_waitcnt vmcnt(12)
	v_mfma_f32_16x16x32_bf16 v[62:65], v[116:119], v[10:13], v[62:65]
	s_waitcnt vmcnt(11)
	v_mfma_f32_16x16x32_bf16 v[54:57], v[120:123], v[10:13], v[54:57]
	s_waitcnt vmcnt(10)
	v_mfma_f32_16x16x32_bf16 v[58:61], v[124:127], v[10:13], v[58:61]
	s_waitcnt vmcnt(9)
	v_mfma_f32_16x16x32_bf16 v[94:97], v[128:131], v[10:13], v[94:97]
	s_waitcnt vmcnt(8)
	v_mfma_f32_16x16x32_bf16 v[90:93], v[138:141], v[10:13], v[90:93]
	s_waitcnt vmcnt(7)
	v_mfma_f32_16x16x32_bf16 v[66:69], v[22:25], v[6:9], v[66:69]
	s_waitcnt vmcnt(6)
	v_mfma_f32_16x16x32_bf16 v[70:73], v[26:29], v[6:9], v[70:73]
	s_waitcnt vmcnt(5)
	v_mfma_f32_16x16x32_bf16 v[74:77], v[30:33], v[6:9], v[74:77]
	s_waitcnt vmcnt(4)
	v_mfma_f32_16x16x32_bf16 v[62:65], v[34:37], v[6:9], v[62:65]
	s_waitcnt vmcnt(3)
	v_mfma_f32_16x16x32_bf16 v[54:57], v[38:41], v[6:9], v[54:57]
	s_waitcnt vmcnt(2)
	v_mfma_f32_16x16x32_bf16 v[58:61], v[42:45], v[6:9], v[58:61]
	s_waitcnt vmcnt(1)
	v_mfma_f32_16x16x32_bf16 v[94:97], v[46:49], v[6:9], v[94:97]
	s_waitcnt vmcnt(0)
	v_mfma_f32_16x16x32_bf16 v[90:93], v[100:103], v[6:9], v[90:93]
	s_branch .LBB0_405

; DI f32x4 mfma32(bf16x8 a, bf16x8 b, f32x4 c) { return __builtin_amdgcn_mfma_f32_16x16x32_bf16(a, b, c, 0, 0, 0); }
; DI void phase_hg3(const Ctx& c, LAS unsigned char* lds, int g, int l, const bf16* PROJ, const bf16* ST, const bf16* RT, const float* GC, const bf16* KT1, const bf16* QTB, bf16* MIX, int bid, int nb, int tid) {
;     ...
; #pragma unroll
;             for (int ks = 0; ks < 4; ++ks) {
;                 if (ks < 3) {
; #pragma unroll
;                     for (int vt = 0; vt < 8; ++vt) sa[(ks + 1) & 1][vt] = *(const bf16x8*)(ST + su * 16384 + ((vt * 4 + ks + 1) * 64 + lane) * 8); }
; #pragma unroll
;                 for (int vt = 0; vt < 8; ++vt) o[vt] = mfma32(sa[ks & 1][vt], qt[ks], o[vt]);
;             }
;             { const int sq_ = cgk / ncs, cs = cgk - sq_ * ncs, p = dir ? ncs - 1 - cs : cs, blk = p >> 3;
;               if (blk > 0) { const size_t rr = (size_t)((sq_ * 8 + h * 2 + dir) * rps + blk);
.LBB0_409:
	s_or_b64 exec, exec, vcc
	s_waitcnt vmcnt(7)
	v_add_co_u32_e32 v86, vcc, 0x1000, v184
	s_waitcnt vmcnt(6)
	v_mfma_f32_16x16x32_bf16 v[46:49], v[46:49], v[42:45], v[78:81]
	v_addc_co_u32_e32 v87, vcc, 0, v185, vcc
	s_movk_i32 s1, 0x4000
	s_nop 0
	v_add_co_u32_e32 v78, vcc, 0x2000, v184
	s_waitcnt vmcnt(5)
	v_mfma_f32_16x16x32_bf16 v[38:41], v[38:41], v[42:45], v[70:73]
	v_addc_co_u32_e32 v79, vcc, 0, v185, vcc
	v_add_co_u32_e32 v88, vcc, 0x3000, v184
	s_nop 0
	global_load_dwordx4 v[70:73], v[86:87], off offset:1024
	v_addc_co_u32_e32 v89, vcc, 0, v185, vcc
	v_mfma_f32_16x16x32_bf16 v[50:53], v[50:53], v[42:45], v[82:85]
	v_add_co_u32_e32 v90, vcc, s1, v184
	s_movk_i32 s19, 0x6000
	s_nop 0
	global_load_dwordx4 v[82:85], v[184:185], off offset:1024
	s_waitcnt vmcnt(6)
	v_mfma_f32_16x16x32_bf16 v[34:37], v[34:37], v[42:45], v[66:69]
	v_addc_co_u32_e32 v91, vcc, 0, v185, vcc
	v_add_co_u32_e32 v92, vcc, 0x5000, v184
	s_nop 0
	global_load_dwordx4 v[66:69], v[78:79], off offset:1024
	s_waitcnt vmcnt(4)
	v_mfma_f32_16x16x32_bf16 v[22:25], v[22:25], v[42:45], v[58:61]
	v_addc_co_u32_e32 v93, vcc, 0, v185, vcc
	v_add_co_u32_e32 v94, vcc, s19, v184
	s_nop 0
	global_load_dwordx4 v[58:61], v[88:89], off offset:1024
	v_mfma_f32_16x16x32_bf16 v[30:33], v[30:33], v[42:45], v[74:77]
	v_addc_co_u32_e32 v95, vcc, 0, v185, vcc
	s_not_b32 s0, s33
	v_mfma_f32_16x16x32_bf16 v[26:29], v[26:29], v[42:45], v[62:65]
	v_readlane_b32 s33, v254, 53
	s_add_i32 s0, s33, s0
	s_ashr_i32 s0, s0, 3
	s_waitcnt vmcnt(4)
	v_mfma_f32_16x16x32_bf16 v[18:21], v[18:21], v[42:45], v[54:57]
	s_nop 2
	global_load_dwordx4 v[54:57], v[184:185], off offset:2048
	global_load_dwordx4 v[62:65], v[184:185], off offset:3072
	global_load_dwordx4 v[74:77], v[78:79], off offset:2048
	s_cmp_lt_i32 s0, 1
	s_waitcnt vmcnt(5)
	v_mfma_f32_16x16x32_bf16 v[50:53], v[82:85], v[14:17], v[50:53]
	v_mfma_f32_16x16x32_bf16 v[46:49], v[70:73], v[14:17], v[46:49]
	global_load_dwordx4 v[70:73], v[78:79], off offset:3072
	s_nop 0
	global_load_dwordx4 v[78:81], v[90:91], off offset:1024
	s_waitcnt vmcnt(6)
	v_mfma_f32_16x16x32_bf16 v[38:41], v[66:69], v[14:17], v[38:41]
	s_waitcnt vmcnt(5)
	v_mfma_f32_16x16x32_bf16 v[34:37], v[58:61], v[14:17], v[34:37]
	global_load_dwordx4 v[58:61], v[92:93], off offset:1024
	global_load_dwordx4 v[66:69], v[86:87], off offset:2048
	s_waitcnt vmcnt(6)
	v_mfma_f32_16x16x32_bf16 v[50:53], v[54:57], v[10:13], v[50:53]
	global_load_dwordx4 v[54:57], v[90:91], off offset:2048
	s_waitcnt vmcnt(5)
	v_mfma_f32_16x16x32_bf16 v[38:41], v[74:77], v[10:13], v[38:41]
	v_mfma_f32_16x16x32_bf16 v[50:53], v[62:65], v[6:9], v[50:53]
	s_waitcnt vmcnt(4)
	v_mfma_f32_16x16x32_bf16 v[38:41], v[70:73], v[6:9], v[38:41]
	s_waitcnt vmcnt(3)
	v_mfma_f32_16x16x32_bf16 v[30:33], v[78:81], v[14:17], v[30:33]
	global_load_dwordx4 v[78:81], v[90:91], off offset:3072
	v_add_co_u32_e32 v90, vcc, 0x7000, v184
	s_waitcnt vmcnt(3)
	v_mfma_f32_16x16x32_bf16 v[26:29], v[58:61], v[14:17], v[26:29]
	global_load_dwordx4 v[58:61], v[94:95], off offset:1024
	global_load_dwordx4 v[82:85], v[86:87], off offset:3072
	v_addc_co_u32_e32 v91, vcc, 0, v185, vcc
	s_waitcnt vmcnt(4)
	v_mfma_f32_16x16x32_bf16 v[46:49], v[66:69], v[10:13], v[46:49]
	global_load_dwordx4 v[66:69], v[94:95], off offset:2048
	s_waitcnt vmcnt(4)
	v_mfma_f32_16x16x32_bf16 v[30:33], v[54:57], v[10:13], v[30:33]
	s_waitcnt vmcnt(2)
	v_mfma_f32_16x16x32_bf16 v[22:25], v[58:61], v[14:17], v[22:25]
	global_load_dwordx4 v[58:61], v[90:91], off offset:1024
	global_load_dwordx4 v[74:77], v[94:95], off offset:3072
	s_waitcnt vmcnt(2)
	v_mfma_f32_16x16x32_bf16 v[22:25], v[66:69], v[10:13], v[22:25]
	v_mfma_f32_16x16x32_bf16 v[46:49], v[82:85], v[6:9], v[46:49]
	v_mfma_f32_16x16x32_bf16 v[30:33], v[78:81], v[6:9], v[30:33]
	s_waitcnt vmcnt(1)
	v_mfma_f32_16x16x32_bf16 v[18:21], v[58:61], v[14:17], v[18:21]
	global_load_dwordx4 v[58:61], v[88:89], off offset:2048
	s_nop 0
	global_load_dwordx4 v[86:89], v[88:89], off offset:3072
	s_waitcnt vmcnt(2)
	v_mfma_f32_16x16x32_bf16 v[22:25], v[74:77], v[6:9], v[22:25]
	s_waitcnt vmcnt(1)
	v_mfma_f32_16x16x32_bf16 v[34:37], v[58:61], v[10:13], v[34:37]
	global_load_dwordx4 v[54:57], v[92:93], off offset:2048
	global_load_dwordx4 v[58:61], v[92:93], off offset:3072
	global_load_dwordx4 v[66:69], v[90:91], off offset:3072
	s_waitcnt vmcnt(2)
	v_mfma_f32_16x16x32_bf16 v[26:29], v[54:57], v[10:13], v[26:29]
	global_load_dwordx4 v[54:57], v[90:91], off offset:2048
	v_mfma_f32_16x16x32_bf16 v[34:37], v[86:89], v[6:9], v[34:37]
	s_waitcnt vmcnt(2)
	v_mfma_f32_16x16x32_bf16 v[26:29], v[58:61], v[6:9], v[26:29]
	s_waitcnt vmcnt(0)
	v_mfma_f32_16x16x32_bf16 v[18:21], v[54:57], v[10:13], v[18:21]
	v_mfma_f32_16x16x32_bf16 v[18:21], v[66:69], v[6:9], v[18:21]
	s_cbranch_scc1 .LBB0_395
; DI f32x4 mfma32(bf16x8 a, bf16x8 b, f32x4 c) { return __builtin_amdgcn_mfma_f32_16x16x32_bf16(a, b, c, 0, 0, 0); }
; DI void phase_hg3(const Ctx& c, LAS unsigned char* lds, int g, int l, const bf16* PROJ, const bf16* ST, const bf16* RT, const float* GC, const bf16* KT1, const bf16* QTB, bf16* MIX, int bid, int nb, int tid) {
;     ...
;             { const int sq_ = cgk / ncs, cs = cgk - sq_ * ncs, p = dir ? ncs - 1 - cs : cs, blk = p >> 3;
;               if (blk > 0) { const size_t rr = (size_t)((sq_ * 8 + h * 2 + dir) * rps + blk);
; #pragma unroll
;                 for (int ks = 0; ks < 4; ++ks) { const float* gp = GC + su * 128 + ks * 32 + gq * 8; const bf16x8 q2 = scale8(qt[ks], *(const f32x4*)gp, *(const f32x4*)(gp + 4));
; #pragma unroll
;                     for (int vt = 0; vt < 8; ++vt) sa[0][vt] = *(const bf16x8*)(RT + rr * 16384 + ((vt * 4 + ks) * 64 + lane) * 8);
; #pragma unroll
;                     for (int vt = 0; vt < 8; ++vt) o[vt] = mfma32(sa[0][vt], q2, o[vt]); } } }
	v_or_b32_e32 v54, 1, v181
	v_readlane_b32 s33, v254, 44
	s_nop 1
	v_lshlrev_b32_e32 v54, s33, v54
	v_add_u32_e32 v56, s0, v54
	v_lshlrev_b64 v[54:55], 9, v[182:183]
	v_ashrrev_i32_e32 v57, 31, v56
	v_lshl_add_u64 v[54:55], v[2:3], 0, v[54:55]
	v_lshlrev_b64 v[68:69], 15, v[56:57]
	v_lshl_add_u64 v[56:57], v[146:147], 0, v[68:69]
	s_movk_i32 s0, 0x3000
	s_mov_b64 vcc, 0x1000
	v_lshl_add_u64 v[58:59], vcc, 0, v[56:57]
	s_mov_b64 vcc, 0x3000
	v_lshl_add_u64 v[60:61], vcc, 0, v[56:57]
	s_mov_b64 vcc, 0x5000
	v_lshl_add_u64 v[62:63], vcc, 0, v[56:57]
	s_mov_b64 vcc, 0x7000
	v_lshl_add_u64 v[72:73], vcc, 0, v[56:57]
	global_load_dwordx4 v[64:67], v[54:55], off offset:16
	global_load_dwordx4 v[68:71], v[54:55], off
	global_load_dwordx4 v[74:77], v[54:55], off offset:144
	global_load_dwordx4 v[78:81], v[54:55], off offset:128
	global_load_dwordx4 v[82:85], v[54:55], off offset:272
	global_load_dwordx4 v[86:89], v[54:55], off offset:256
	global_load_dwordx4 v[90:93], v[54:55], off offset:400
	global_load_dwordx4 v[94:97], v[54:55], off offset:384
	global_load_dwordx4 v[98:101], v[58:59], off offset:-4096
	global_load_dwordx4 v[102:105], v[58:59], off
	global_load_dwordx4 v[106:109], v[60:61], off offset:-4096
	global_load_dwordx4 v[110:113], v[60:61], off
	global_load_dwordx4 v[114:117], v[62:63], off offset:-4096
	global_load_dwordx4 v[118:121], v[62:63], off
	global_load_dwordx4 v[122:125], v[72:73], off offset:-4096
	global_load_dwordx4 v[126:129], v[72:73], off
	s_waitcnt vmcnt(8)
	v_lshlrev_b32_e32 v130, 16, v42
	v_and_b32_e32 v131, 0xffff0000, v42
	v_lshlrev_b32_e32 v132, 16, v43
	v_and_b32_e32 v133, 0xffff0000, v43
	v_pk_mul_f32 v[130:131], v[68:69], v[130:131]
	v_pk_mul_f32 v[132:133], v[70:71], v[132:133]
	v_cvt_pk_bf16_f32 v42, v130, v131
	v_cvt_pk_bf16_f32 v43, v132, v133
	v_lshlrev_b32_e32 v130, 16, v44
	v_and_b32_e32 v131, 0xffff0000, v44
	v_lshlrev_b32_e32 v132, 16, v45
	v_and_b32_e32 v133, 0xffff0000, v45
	v_pk_mul_f32 v[130:131], v[64:65], v[130:131]
	v_pk_mul_f32 v[132:133], v[66:67], v[132:133]
	v_cvt_pk_bf16_f32 v44, v130, v131
	v_cvt_pk_bf16_f32 v45, v132, v133
	v_lshlrev_b32_e32 v130, 16, v14
	v_and_b32_e32 v131, 0xffff0000, v14
	v_lshlrev_b32_e32 v132, 16, v15
	v_and_b32_e32 v133, 0xffff0000, v15
	v_pk_mul_f32 v[130:131], v[78:79], v[130:131]
	v_pk_mul_f32 v[132:133], v[80:81], v[132:133]
	v_cvt_pk_bf16_f32 v14, v130, v131
	v_cvt_pk_bf16_f32 v15, v132, v133
	v_lshlrev_b32_e32 v130, 16, v16
	v_and_b32_e32 v131, 0xffff0000, v16
	v_lshlrev_b32_e32 v132, 16, v17
	v_and_b32_e32 v133, 0xffff0000, v17
	v_pk_mul_f32 v[130:131], v[74:75], v[130:131]
	v_pk_mul_f32 v[132:133], v[76:77], v[132:133]
	v_cvt_pk_bf16_f32 v16, v130, v131
	v_cvt_pk_bf16_f32 v17, v132, v133
	v_lshlrev_b32_e32 v130, 16, v10
	v_and_b32_e32 v131, 0xffff0000, v10
	v_lshlrev_b32_e32 v132, 16, v11
	v_and_b32_e32 v133, 0xffff0000, v11
	v_pk_mul_f32 v[130:131], v[86:87], v[130:131]
	v_pk_mul_f32 v[132:133], v[88:89], v[132:133]
	v_cvt_pk_bf16_f32 v10, v130, v131
	v_cvt_pk_bf16_f32 v11, v132, v133
	v_lshlrev_b32_e32 v130, 16, v12
	v_and_b32_e32 v131, 0xffff0000, v12
	v_lshlrev_b32_e32 v132, 16, v13
	v_and_b32_e32 v133, 0xffff0000, v13
	v_pk_mul_f32 v[130:131], v[82:83], v[130:131]
	v_pk_mul_f32 v[132:133], v[84:85], v[132:133]
	v_cvt_pk_bf16_f32 v12, v130, v131
	v_cvt_pk_bf16_f32 v13, v132, v133
	v_lshlrev_b32_e32 v130, 16, v6
	v_and_b32_e32 v131, 0xffff0000, v6
	v_lshlrev_b32_e32 v132, 16, v7
	v_and_b32_e32 v133, 0xffff0000, v7
	v_pk_mul_f32 v[130:131], v[94:95], v[130:131]
	v_pk_mul_f32 v[132:133], v[96:97], v[132:133]
	v_cvt_pk_bf16_f32 v6, v130, v131
	v_cvt_pk_bf16_f32 v7, v132, v133
	v_lshlrev_b32_e32 v130, 16, v8
	v_and_b32_e32 v131, 0xffff0000, v8
	v_lshlrev_b32_e32 v132, 16, v9
	v_and_b32_e32 v133, 0xffff0000, v9
	v_pk_mul_f32 v[130:131], v[90:91], v[130:131]
	v_pk_mul_f32 v[132:133], v[92:93], v[132:133]
	v_cvt_pk_bf16_f32 v8, v130, v131
	v_cvt_pk_bf16_f32 v9, v132, v133
	global_load_dwordx4 v[64:67], v[58:59], off offset:-3072
	global_load_dwordx4 v[68:71], v[58:59], off offset:1024
	global_load_dwordx4 v[74:77], v[60:61], off offset:-3072
	global_load_dwordx4 v[78:81], v[60:61], off offset:1024
	global_load_dwordx4 v[82:85], v[62:63], off offset:-3072
	global_load_dwordx4 v[86:89], v[62:63], off offset:1024
	global_load_dwordx4 v[90:93], v[72:73], off offset:-3072
	global_load_dwordx4 v[94:97], v[72:73], off offset:1024
	s_waitcnt vmcnt(15)
; DI f32x4 mfma32(bf16x8 a, bf16x8 b, f32x4 c) { return __builtin_amdgcn_mfma_f32_16x16x32_bf16(a, b, c, 0, 0, 0); }
; DI void phase_hg3(const Ctx& c, LAS unsigned char* lds, int g, int l, const bf16* PROJ, const bf16* ST, const bf16* RT, const float* GC, const bf16* KT1, const bf16* QTB, bf16* MIX, int bid, int nb, int tid) {
;     ...
;                 for (int ks = 0; ks < 4; ++ks) { const float* gp = GC + su * 128 + ks * 32 + gq * 8; const bf16x8 q2 = scale8(qt[ks], *(const f32x4*)gp, *(const f32x4*)(gp + 4));
; #pragma unroll
;                     for (int vt = 0; vt < 8; ++vt) sa[0][vt] = *(const bf16x8*)(RT + rr * 16384 + ((vt * 4 + ks) * 64 + lane) * 8);
; #pragma unroll
;                     for (int vt = 0; vt < 8; ++vt) o[vt] = mfma32(sa[0][vt], q2, o[vt]); } } }
	v_mfma_f32_16x16x32_bf16 v[50:53], v[98:101], v[42:45], v[50:53]
	s_waitcnt vmcnt(14)
	v_mfma_f32_16x16x32_bf16 v[46:49], v[102:105], v[42:45], v[46:49]
	s_waitcnt vmcnt(13)
	v_mfma_f32_16x16x32_bf16 v[38:41], v[106:109], v[42:45], v[38:41]
	s_waitcnt vmcnt(12)
	v_mfma_f32_16x16x32_bf16 v[34:37], v[110:113], v[42:45], v[34:37]
	s_waitcnt vmcnt(11)
	v_mfma_f32_16x16x32_bf16 v[30:33], v[114:117], v[42:45], v[30:33]
	s_waitcnt vmcnt(10)
	v_mfma_f32_16x16x32_bf16 v[26:29], v[118:121], v[42:45], v[26:29]
	s_waitcnt vmcnt(9)
	v_mfma_f32_16x16x32_bf16 v[22:25], v[122:125], v[42:45], v[22:25]
	s_waitcnt vmcnt(8)
	v_mfma_f32_16x16x32_bf16 v[18:21], v[126:129], v[42:45], v[18:21]
	global_load_dwordx4 v[98:101], v[58:59], off offset:-2048
	global_load_dwordx4 v[102:105], v[58:59], off offset:2048
	global_load_dwordx4 v[106:109], v[60:61], off offset:-2048
	global_load_dwordx4 v[110:113], v[60:61], off offset:2048
	global_load_dwordx4 v[114:117], v[62:63], off offset:-2048
	global_load_dwordx4 v[118:121], v[62:63], off offset:2048
	global_load_dwordx4 v[122:125], v[72:73], off offset:-2048
	global_load_dwordx4 v[126:129], v[72:73], off offset:2048
	s_waitcnt vmcnt(15)
	v_mfma_f32_16x16x32_bf16 v[50:53], v[64:67], v[14:17], v[50:53]
	s_waitcnt vmcnt(14)
	v_mfma_f32_16x16x32_bf16 v[46:49], v[68:71], v[14:17], v[46:49]
	s_waitcnt vmcnt(13)
	v_mfma_f32_16x16x32_bf16 v[38:41], v[74:77], v[14:17], v[38:41]
	s_waitcnt vmcnt(12)
	v_mfma_f32_16x16x32_bf16 v[34:37], v[78:81], v[14:17], v[34:37]
	s_waitcnt vmcnt(11)
	v_mfma_f32_16x16x32_bf16 v[30:33], v[82:85], v[14:17], v[30:33]
	s_waitcnt vmcnt(10)
	v_mfma_f32_16x16x32_bf16 v[26:29], v[86:89], v[14:17], v[26:29]
	s_waitcnt vmcnt(9)
	v_mfma_f32_16x16x32_bf16 v[22:25], v[90:93], v[14:17], v[22:25]
	s_waitcnt vmcnt(8)
	v_mfma_f32_16x16x32_bf16 v[18:21], v[94:97], v[14:17], v[18:21]
	global_load_dwordx4 v[64:67], v[58:59], off offset:-1024
	global_load_dwordx4 v[68:71], v[58:59], off offset:3072
	global_load_dwordx4 v[74:77], v[60:61], off offset:-1024
	global_load_dwordx4 v[78:81], v[60:61], off offset:3072
	global_load_dwordx4 v[82:85], v[62:63], off offset:-1024
	global_load_dwordx4 v[86:89], v[62:63], off offset:3072
	global_load_dwordx4 v[90:93], v[72:73], off offset:-1024
	global_load_dwordx4 v[94:97], v[72:73], off offset:3072
	s_waitcnt vmcnt(15)
	v_mfma_f32_16x16x32_bf16 v[50:53], v[98:101], v[10:13], v[50:53]
	s_waitcnt vmcnt(14)
	v_mfma_f32_16x16x32_bf16 v[46:49], v[102:105], v[10:13], v[46:49]
	s_waitcnt vmcnt(13)
	v_mfma_f32_16x16x32_bf16 v[38:41], v[106:109], v[10:13], v[38:41]
	s_waitcnt vmcnt(12)
	v_mfma_f32_16x16x32_bf16 v[34:37], v[110:113], v[10:13], v[34:37]
	s_waitcnt vmcnt(11)
	v_mfma_f32_16x16x32_bf16 v[30:33], v[114:117], v[10:13], v[30:33]
	s_waitcnt vmcnt(10)
	v_mfma_f32_16x16x32_bf16 v[26:29], v[118:121], v[10:13], v[26:29]
	s_waitcnt vmcnt(9)
	v_mfma_f32_16x16x32_bf16 v[22:25], v[122:125], v[10:13], v[22:25]
	s_waitcnt vmcnt(8)
	v_mfma_f32_16x16x32_bf16 v[18:21], v[126:129], v[10:13], v[18:21]
	s_waitcnt vmcnt(7)
	v_mfma_f32_16x16x32_bf16 v[50:53], v[64:67], v[6:9], v[50:53]
	s_waitcnt vmcnt(6)
	v_mfma_f32_16x16x32_bf16 v[46:49], v[68:71], v[6:9], v[46:49]
	s_waitcnt vmcnt(5)
	v_mfma_f32_16x16x32_bf16 v[38:41], v[74:77], v[6:9], v[38:41]
	s_waitcnt vmcnt(4)
	v_mfma_f32_16x16x32_bf16 v[34:37], v[78:81], v[6:9], v[34:37]
	s_waitcnt vmcnt(3)
	v_mfma_f32_16x16x32_bf16 v[30:33], v[82:85], v[6:9], v[30:33]
	s_waitcnt vmcnt(2)
	v_mfma_f32_16x16x32_bf16 v[26:29], v[86:89], v[6:9], v[26:29]
	s_waitcnt vmcnt(1)
	v_mfma_f32_16x16x32_bf16 v[22:25], v[90:93], v[6:9], v[22:25]
	s_waitcnt vmcnt(0)
	v_mfma_f32_16x16x32_bf16 v[18:21], v[94:97], v[6:9], v[18:21]
	s_branch .LBB0_395

;     __device__ __forceinline__ void operator()(const f32x4 (&acc_)[2][2][4][2], const Unit& u, int wr, int wc, int fr, int fq) const {
;     ...
;                     const f32x4 w0 = *(const PG8_LAS f32x4*)(wl + jj + 4 * n), w1 = *(const PG8_LAS f32x4*)(wl + 128 + jj + 4 * n), w2 = *(const PG8_LAS f32x4*)(wl + 256 + jj + 4 * n), bb = *(const PG8_LAS f32x4*)(wl + 384 + jj + 4 * n);
;                     f32x4 bp = {0.f, 0.f, 0.f, 0.f}, bn = {0.f, 0.f, 0.f, 0.f};
;                     if (m == 0 && sp >= 0) bp = *(const PG8_LAS f32x4*)(xg + sp * 128 + jj + 4 * n) * xg[1536 + ai * HALF + wr * 64 - 1];
;                     if (m == 3 && sn >= 0) bn = *(const PG8_LAS f32x4*)(xg + sn * 128 + jj + 4 * n) * xg[1536 + ai * HALF + wr * 64 + 64];
; #pragma unroll
;                     for (int eh = 0; eh < 2; ++eh) { v2f gv, p, q, up;
; #pragma unroll
;                         for (int k = 0; k < 2; ++k) { const int e = 2 * eh + k; const float g0 = acc[ai][0][m][n][e];
;                             const float pa = m > 0 ? dpp_ror1(acc[ai][0][m > 0 ? m - 1 : 0][n][e]) : bp[e];
;                             const float qa = m < 3 ? dpp_ror15(acc[ai][0][m < 3 ? m + 1 : 3][n][e]) : bn[e];
;                             gv[k] = g0; up[k] = acc[ai][1][m][n][e];
;                             p[k] = __builtin_bit_cast(float, __builtin_amdgcn_update_dpp(__builtin_bit_cast(int, pa), __builtin_bit_cast(int, g0), 0x111, 0xf, 0xf, false));
;                             q[k] = __builtin_bit_cast(float, __builtin_amdgcn_update_dpp(__builtin_bit_cast(int, qa), __builtin_bit_cast(int, g0), 0x101, 0xf, 0xf, false)); }
;                         const v2f a0 = (v2f){w0[2 * eh], w0[2 * eh + 1]} * mp, a1 = (v2f){w1[2 * eh], w1[2 * eh + 1]}, a2 = (v2f){w2[2 * eh], w2[2 * eh + 1]} * mn, ab = (v2f){bb[2 * eh], bb[2 * eh + 1]};
;                         const v2f x = a0 * p + (a1 * gv + (a2 * q + ab));
;                         const v2f arg = x * ((x * x) * (-0.10294324f) + (-2.3022082f));
;                         v2f ex; ex[0] = __builtin_amdgcn_exp2f(arg[0]); ex[1] = __builtin_amdgcn_exp2f(arg[1]);
;                         const v2f dn = ex + 1.0f; v2f rc; rc[0] = __builtin_amdgcn_rcpf(dn[0]); rc[1] = __builtin_amdgcn_rcpf(dn[1]);
;                         const v2f y = (x * rc) * up;
;                         ov[2 * n + eh] = cvt_pk_bf16(y[0], y[1]); }
.LBB0_659:
	s_waitcnt lgkmcnt(5)
	v_pk_mul_f32 v[190:191], v[64:65], v[198:199] op_sel_hi:[1,0]
	v_pk_mul_f32 v[192:193], v[62:63], v[198:199] op_sel_hi:[1,0]
	v_pk_mul_f32 v[184:185], v[68:69], v[188:189] op_sel_hi:[1,0]
	v_pk_mul_f32 v[186:187], v[66:67], v[188:189] op_sel_hi:[1,0]
	ds_read_b128 v[74:77], v235 offset:16
	ds_read_b128 v[62:65], v236 offset:16
	ds_read_b128 v[70:73], v237 offset:16
	ds_read_b128 v[66:69], v238 offset:16
	v_mov_b32_dpp v212, v186 row_ror:15 row_mask:0xf bank_mask:0xf
	v_mov_b32_dpp v213, v187 row_ror:15 row_mask:0xf bank_mask:0xf
	v_mov_b32_dpp v206, v184 row_ror:15 row_mask:0xf bank_mask:0xf
	v_mov_b32_dpp v207, v185 row_ror:15 row_mask:0xf bank_mask:0xf
	v_mov_b32_dpp v208, v192 row_shr:1 row_mask:0xf bank_mask:0xf
	v_mov_b32_dpp v212, v192 row_shl:1 row_mask:0xf bank_mask:0xf
	v_mov_b32_dpp v209, v193 row_shr:1 row_mask:0xf bank_mask:0xf
	v_mov_b32_dpp v213, v193 row_shl:1 row_mask:0xf bank_mask:0xf
	v_mov_b32_dpp v204, v190 row_shr:1 row_mask:0xf bank_mask:0xf
	v_mov_b32_dpp v206, v190 row_shl:1 row_mask:0xf bank_mask:0xf
	v_mov_b32_dpp v205, v191 row_shr:1 row_mask:0xf bank_mask:0xf
	v_mov_b32_dpp v207, v191 row_shl:1 row_mask:0xf bank_mask:0xf
	s_and_b64 vcc, exec, s[44:45]
	v_mov_b32_e32 v201, 0
	v_mov_b32_e32 v202, 0
	v_mov_b32_e32 v203, 0
	s_cbranch_vccnz .LBB0_661
	v_mov_b32_e32 v160, s79
	ds_read_b128 v[194:197], v239 offset:16
	ds_read_b32 v160, v160 offset:6140
	s_waitcnt lgkmcnt(0)
	v_pk_mul_f32 v[202:203], v[196:197], v[160:161] op_sel_hi:[1,0]
	v_pk_mul_f32 v[200:201], v[194:195], v[160:161] op_sel_hi:[1,0]
.LBB0_661:
	v_mov_b32_e32 v199, v198
	v_mov_b32_e32 v189, v188
	v_mov_b32_e32 v210, v198
	v_mov_b32_e32 v211, v198
	v_pk_mul_f32 v[196:197], v[146:147], v[198:199]
	v_mov_b32_e32 v146, v188
	v_mov_b32_e32 v147, v188
	v_add_u32_e32 v181, s33, v5
	v_pk_mul_f32 v[194:195], v[148:149], v[210:211]
	v_pk_mul_f32 v[146:147], v[156:157], v[146:147]
	v_pk_mul_f32 v[148:149], v[154:155], v[188:189]
	v_mov_b32_e32 v155, v0
	v_or_b32_e32 v176, s1, v218
	v_mov_b32_dpp v156, v148 row_ror:15 row_mask:0xf bank_mask:0xf
	v_mov_b32_dpp v157, v149 row_ror:15 row_mask:0xf bank_mask:0xf
	v_mov_b32_dpp v154, v146 row_ror:15 row_mask:0xf bank_mask:0xf
	v_mov_b32_dpp v155, v147 row_ror:15 row_mask:0xf bank_mask:0xf
	v_cmp_gt_i32_e32 vcc, s26, v181
	v_ashrrev_i32_e32 v177, 31, v176
	v_mov_b32_dpp v200, v196 row_shr:1 row_mask:0xf bank_mask:0xf
	v_mov_b32_dpp v156, v196 row_shl:1 row_mask:0xf bank_mask:0xf
	v_mov_b32_dpp v201, v197 row_shr:1 row_mask:0xf bank_mask:0xf
	v_mov_b32_dpp v157, v197 row_shl:1 row_mask:0xf bank_mask:0xf
	v_mov_b32_dpp v202, v194 row_shr:1 row_mask:0xf bank_mask:0xf
	v_mov_b32_dpp v154, v194 row_shl:1 row_mask:0xf bank_mask:0xf
	v_mov_b32_dpp v203, v195 row_shr:1 row_mask:0xf bank_mask:0xf
	v_mov_b32_dpp v155, v195 row_shl:1 row_mask:0xf bank_mask:0xf
	s_and_b64 s[0:1], s[6:7], vcc
	s_and_saveexec_b64 s[46:47], s[0:1]
	s_cbranch_execz .LBB0_663
	v_and_b32_e32 v161, s34, v181
	v_cmp_eq_u32_e32 vcc, 0, v161
	s_mov_b32 s0, 0xc0135761
	v_pk_mul_f32 v[150:151], v[150:151], v[198:199]
	v_cndmask_b32_e64 v160, 1.0, 0, vcc
	v_cmp_eq_u32_e32 vcc, s34, v161
	s_waitcnt lgkmcnt(7)
	v_pk_mul_f32 v[244:245], v[160:161], v[50:51] op_sel_hi:[0,1]
	v_pk_mul_f32 v[152:153], v[152:153], v[210:211]
	v_cndmask_b32_e64 v214, 1.0, 0, vcc
	s_waitcnt lgkmcnt(5)
	v_pk_mul_f32 v[246:247], v[214:215], v[54:55] op_sel_hi:[0,1]
	s_waitcnt lgkmcnt(4)
	v_pk_fma_f32 v[212:213], v[246:247], v[212:213], v[58:59]
	v_pk_mul_f32 v[142:143], v[142:143], v[198:199]
	v_pk_fma_f32 v[212:213], v[192:193], v[46:47], v[212:213]
	s_waitcnt lgkmcnt(1)
	v_pk_mul_f32 v[198:199], v[214:215], v[70:71] op_sel_hi:[0,1]
	v_pk_fma_f32 v[208:209], v[244:245], v[208:209], v[212:213]
	v_mov_b64_e32 v[244:245], s[0:1]
	v_pk_mul_f32 v[212:213], v[208:209], v[208:209]
	s_mov_b32 s0, 0x3dd2d3e8
	v_pk_fma_f32 v[212:213], v[212:213], s[0:1], v[244:245] op_sel_hi:[1,0,0] neg_lo:[1,0,0] neg_hi:[1,0,0]
	s_waitcnt lgkmcnt(0)
	v_pk_fma_f32 v[156:157], v[198:199], v[156:157], v[66:67]
	v_pk_mul_f32 v[212:213], v[208:209], v[212:213]
	v_pk_fma_f32 v[156:157], v[196:197], v[62:63], v[156:157]
	v_exp_f32_e32 v212, v212
	v_exp_f32_e32 v213, v213
	v_pk_mul_f32 v[144:145], v[144:145], v[210:211]
	v_pk_add_f32 v[212:213], v[212:213], 1.0 op_sel_hi:[1,0]
	s_nop 0
	v_rcp_f32_e32 v212, v212
	v_rcp_f32_e32 v213, v213
	s_nop 0
	v_pk_mul_f32 v[208:209], v[208:209], v[212:213]
	v_pk_mul_f32 v[212:213], v[214:215], v[56:57] op_sel_hi:[0,1]
	v_pk_fma_f32 v[206:207], v[212:213], v[206:207], v[60:61]
	v_pk_mul_f32 v[150:151], v[150:151], v[208:209]
	v_pk_mul_f32 v[208:209], v[160:161], v[52:53] op_sel_hi:[0,1]
	v_pk_fma_f32 v[206:207], v[190:191], v[48:49], v[206:207]
	v_cvt_pk_bf16_f32 v150, v150, v151
	v_pk_fma_f32 v[204:205], v[208:209], v[204:205], v[206:207]
	s_nop 0
	v_pk_mul_f32 v[206:207], v[204:205], v[204:205]
	s_nop 0
	v_pk_fma_f32 v[206:207], v[206:207], s[0:1], v[244:245] op_sel_hi:[1,0,0] neg_lo:[1,0,0] neg_hi:[1,0,0]
	s_nop 0
	v_pk_mul_f32 v[206:207], v[204:205], v[206:207]
	s_nop 0
	v_exp_f32_e32 v206, v206
	v_exp_f32_e32 v207, v207
	s_nop 0
	v_pk_add_f32 v[206:207], v[206:207], 1.0 op_sel_hi:[1,0]
	s_nop 0
	v_rcp_f32_e32 v206, v206
	v_rcp_f32_e32 v207, v207
	s_nop 0
	v_pk_mul_f32 v[204:205], v[204:205], v[206:207]
	s_nop 0
	v_pk_mul_f32 v[152:153], v[152:153], v[204:205]
	s_nop 0
	v_cvt_pk_bf16_f32 v151, v152, v153
	v_pk_mul_f32 v[152:153], v[160:161], v[74:75] op_sel_hi:[0,1]
	v_pk_fma_f32 v[152:153], v[152:153], v[200:201], v[156:157]
	s_nop 0
	v_pk_mul_f32 v[156:157], v[152:153], v[152:153]
	s_nop 0
; __device__ __forceinline__ unsigned cvt_pk_bf16(float lo, float hi) { const f32x2_t v = {lo, hi}; return __builtin_bit_cast(unsigned, __builtin_convertvector(v, bf2_t)); }
; __device__ __forceinline__ float dpp_ror1(float v)  { return __builtin_bit_cast(float, __builtin_amdgcn_update_dpp(0, __builtin_bit_cast(int, v), 0x121, 0xf, 0xf, false)); }
; __device__ __forceinline__ float dpp_ror15(float v) { return __builtin_bit_cast(float, __builtin_amdgcn_update_dpp(0, __builtin_bit_cast(int, v), 0x12f, 0xf, 0xf, false)); }
;     __device__ __forceinline__ void operator()(const f32x4 (&acc_)[2][2][4][2], const Unit& u, int wr, int wc, int fr, int fq) const {
;     ...
;                         for (int k = 0; k < 2; ++k) { const int e = 2 * eh + k; const float g0 = acc[ai][0][m][n][e];
;                             const float pa = m > 0 ? dpp_ror1(acc[ai][0][m > 0 ? m - 1 : 0][n][e]) : bp[e];
;                             const float qa = m < 3 ? dpp_ror15(acc[ai][0][m < 3 ? m + 1 : 3][n][e]) : bn[e];
;                             gv[k] = g0; up[k] = acc[ai][1][m][n][e];
;                             p[k] = __builtin_bit_cast(float, __builtin_amdgcn_update_dpp(__builtin_bit_cast(int, pa), __builtin_bit_cast(int, g0), 0x111, 0xf, 0xf, false));
;                             q[k] = __builtin_bit_cast(float, __builtin_amdgcn_update_dpp(__builtin_bit_cast(int, qa), __builtin_bit_cast(int, g0), 0x101, 0xf, 0xf, false)); }
;                         const v2f a0 = (v2f){w0[2 * eh], w0[2 * eh + 1]} * mp, a1 = (v2f){w1[2 * eh], w1[2 * eh + 1]}, a2 = (v2f){w2[2 * eh], w2[2 * eh + 1]} * mn, ab = (v2f){bb[2 * eh], bb[2 * eh + 1]};
;                         const v2f x = a0 * p + (a1 * gv + (a2 * q + ab));
;                         const v2f arg = x * ((x * x) * (-0.10294324f) + (-2.3022082f));
;                         v2f ex; ex[0] = __builtin_amdgcn_exp2f(arg[0]); ex[1] = __builtin_amdgcn_exp2f(arg[1]);
;                         const v2f dn = ex + 1.0f; v2f rc; rc[0] = __builtin_amdgcn_rcpf(dn[0]); rc[1] = __builtin_amdgcn_rcpf(dn[1]);
;                         const v2f y = (x * rc) * up;
;                         ov[2 * n + eh] = cvt_pk_bf16(y[0], y[1]); }
;                 }
;                 if (lr >= 1 && lr <= 254 && t < Mtok) *(u32x4*)(ACT + (size_t)t * dff + j) = ov;
	v_pk_fma_f32 v[156:157], v[156:157], s[0:1], v[244:245] op_sel_hi:[1,0,0] neg_lo:[1,0,0] neg_hi:[1,0,0]
	s_nop 0
	v_pk_mul_f32 v[156:157], v[152:153], v[156:157]
	s_nop 0
	v_exp_f32_e32 v156, v156
	v_exp_f32_e32 v157, v157
	s_nop 0
	v_pk_add_f32 v[156:157], v[156:157], 1.0 op_sel_hi:[1,0]
	s_nop 0
	v_rcp_f32_e32 v156, v156
	v_rcp_f32_e32 v157, v157
	s_nop 0
	v_pk_mul_f32 v[152:153], v[152:153], v[156:157]
	v_pk_mul_f32 v[156:157], v[214:215], v[72:73] op_sel_hi:[0,1]
	v_pk_mul_f32 v[142:143], v[142:143], v[152:153]
	v_pk_fma_f32 v[154:155], v[156:157], v[154:155], v[68:69]
	v_cvt_pk_bf16_f32 v152, v142, v143
	v_pk_mul_f32 v[142:143], v[160:161], v[76:77] op_sel_hi:[0,1]
	v_pk_fma_f32 v[154:155], v[194:195], v[64:65], v[154:155]
	s_nop 0
	v_pk_fma_f32 v[142:143], v[142:143], v[202:203], v[154:155]
	s_nop 0
	v_pk_mul_f32 v[154:155], v[142:143], v[142:143]
	s_nop 0
	v_pk_fma_f32 v[154:155], v[154:155], s[0:1], v[244:245] op_sel_hi:[1,0,0] neg_lo:[1,0,0] neg_hi:[1,0,0]
	s_nop 0
	v_pk_mul_f32 v[154:155], v[142:143], v[154:155]
	s_nop 0
	v_exp_f32_e32 v154, v154
	v_exp_f32_e32 v155, v155
	s_nop 0
	v_pk_add_f32 v[154:155], v[154:155], 1.0 op_sel_hi:[1,0]
	s_nop 0
	v_rcp_f32_e32 v154, v154
	v_rcp_f32_e32 v155, v155
	s_nop 0
	v_pk_mul_f32 v[142:143], v[142:143], v[154:155]
	s_nop 0
	v_pk_mul_f32 v[142:143], v[144:145], v[142:143]
	s_nop 0
	v_cvt_pk_bf16_f32 v153, v142, v143
	v_mov_b64_e32 v[142:143], s[18:19]
	v_mad_i64_i32 v[142:143], s[0:1], v181, s27, v[142:143]
	v_lshl_add_u64 v[142:143], v[176:177], 1, v[142:143]
	global_store_dwordx4 v[142:143], v[150:153], off
.LBB0_663:
	s_or_b64 exec, exec, s[46:47]
	v_pk_mul_f32 v[140:141], v[140:141], v[182:183] op_sel_hi:[1,0]
	v_pk_mul_f32 v[138:139], v[138:139], v[182:183] op_sel_hi:[1,0]
	v_pk_mul_f32 v[136:137], v[136:137], v[182:183] op_sel_hi:[1,0]
	v_pk_mul_f32 v[134:135], v[134:135], v[182:183] op_sel_hi:[1,0]
	v_add_u32_e32 v181, s33, v221
	v_mov_b32_dpp v198, v192 row_ror:1 row_mask:0xf bank_mask:0xf
	v_mov_b32_dpp v199, v193 row_ror:1 row_mask:0xf bank_mask:0xf
	v_mov_b32_dpp v192, v138 row_ror:15 row_mask:0xf bank_mask:0xf
	v_mov_b32_dpp v193, v139 row_ror:15 row_mask:0xf bank_mask:0xf
	v_mov_b32_dpp v154, v190 row_ror:1 row_mask:0xf bank_mask:0xf
	v_mov_b32_dpp v156, v140 row_ror:15 row_mask:0xf bank_mask:0xf
	v_mov_b32_dpp v155, v191 row_ror:1 row_mask:0xf bank_mask:0xf
	v_mov_b32_dpp v157, v141 row_ror:15 row_mask:0xf bank_mask:0xf
	v_mov_b32_dpp v150, v196 row_ror:1 row_mask:0xf bank_mask:0xf
	v_mov_b32_dpp v152, v134 row_ror:15 row_mask:0xf bank_mask:0xf
	v_mov_b32_dpp v151, v197 row_ror:1 row_mask:0xf bank_mask:0xf
	v_mov_b32_dpp v153, v135 row_ror:15 row_mask:0xf bank_mask:0xf
	v_mov_b32_dpp v142, v194 row_ror:1 row_mask:0xf bank_mask:0xf
	v_mov_b32_dpp v144, v136 row_ror:15 row_mask:0xf bank_mask:0xf
	v_mov_b32_dpp v143, v195 row_ror:1 row_mask:0xf bank_mask:0xf
	v_mov_b32_dpp v145, v137 row_ror:15 row_mask:0xf bank_mask:0xf
	v_cmp_gt_i32_e32 vcc, s26, v181
	v_mov_b32_dpp v198, v186 row_shr:1 row_mask:0xf bank_mask:0xf
	v_mov_b32_dpp v192, v186 row_shl:1 row_mask:0xf bank_mask:0xf
	v_mov_b32_dpp v199, v187 row_shr:1 row_mask:0xf bank_mask:0xf
	v_mov_b32_dpp v193, v187 row_shl:1 row_mask:0xf bank_mask:0xf
	v_mov_b32_dpp v154, v184 row_shr:1 row_mask:0xf bank_mask:0xf
	v_mov_b32_dpp v156, v184 row_shl:1 row_mask:0xf bank_mask:0xf
	v_mov_b32_dpp v155, v185 row_shr:1 row_mask:0xf bank_mask:0xf
	v_mov_b32_dpp v157, v185 row_shl:1 row_mask:0xf bank_mask:0xf
	v_mov_b32_dpp v150, v148 row_shr:1 row_mask:0xf bank_mask:0xf
	v_mov_b32_dpp v152, v148 row_shl:1 row_mask:0xf bank_mask:0xf
	v_mov_b32_dpp v151, v149 row_shr:1 row_mask:0xf bank_mask:0xf
	v_mov_b32_dpp v153, v149 row_shl:1 row_mask:0xf bank_mask:0xf
	v_mov_b32_dpp v142, v146 row_shr:1 row_mask:0xf bank_mask:0xf
	v_mov_b32_dpp v144, v146 row_shl:1 row_mask:0xf bank_mask:0xf
	v_mov_b32_dpp v143, v147 row_shr:1 row_mask:0xf bank_mask:0xf
	v_mov_b32_dpp v145, v147 row_shl:1 row_mask:0xf bank_mask:0xf
	s_and_b64 s[0:1], s[8:9], vcc
	s_and_saveexec_b64 s[46:47], s[0:1]
	s_cbranch_execz .LBB0_665
	v_and_b32_e32 v183, s34, v181
	v_mov_b32_e32 v160, v188
	v_mov_b32_e32 v161, v188
	v_cmp_eq_u32_e32 vcc, 0, v183
	v_pk_mul_f32 v[132:133], v[132:133], v[160:161]
	v_pk_mul_f32 v[130:131], v[130:131], v[188:189]
	v_pk_mul_f32 v[160:161], v[128:129], v[160:161]
	v_pk_mul_f32 v[128:129], v[126:127], v[188:189]
	v_cndmask_b32_e64 v188, 1.0, 0, vcc
	v_cmp_eq_u32_e32 vcc, s34, v183
	s_waitcnt lgkmcnt(7)
	v_pk_mul_f32 v[126:127], v[188:189], v[50:51] op_sel_hi:[0,1]
	s_mov_b32 s0, 0xc0135761
	v_cndmask_b32_e64 v190, 1.0, 0, vcc
	s_waitcnt lgkmcnt(5)
	v_pk_mul_f32 v[194:195], v[190:191], v[54:55] op_sel_hi:[0,1]
	s_waitcnt lgkmcnt(4)
	v_pk_fma_f32 v[192:193], v[194:195], v[192:193], v[58:59]
	v_mov_b64_e32 v[194:195], s[0:1]
	v_pk_fma_f32 v[192:193], v[186:187], v[46:47], v[192:193]
	s_mov_b32 s0, 0x3dd2d3e8
	v_pk_fma_f32 v[126:127], v[126:127], v[198:199], v[192:193]
	s_nop 0
	v_pk_mul_f32 v[192:193], v[126:127], v[126:127]
	s_nop 0
	v_pk_fma_f32 v[192:193], v[192:193], s[0:1], v[194:195] op_sel_hi:[1,0,0] neg_lo:[1,0,0] neg_hi:[1,0,0]
	s_nop 0
	v_pk_mul_f32 v[192:193], v[126:127], v[192:193]
	s_nop 0
	v_exp_f32_e32 v192, v192
	v_exp_f32_e32 v193, v193
	s_nop 0
	v_pk_add_f32 v[192:193], v[192:193], 1.0 op_sel_hi:[1,0]
	s_nop 0
	v_rcp_f32_e32 v192, v192
	v_rcp_f32_e32 v193, v193
	s_nop 0
	v_pk_mul_f32 v[126:127], v[126:127], v[192:193]
	v_pk_mul_f32 v[192:193], v[190:191], v[56:57] op_sel_hi:[0,1]
	v_pk_fma_f32 v[156:157], v[192:193], v[156:157], v[60:61]
	v_pk_mul_f32 v[126:127], v[130:131], v[126:127]
	v_pk_mul_f32 v[130:131], v[188:189], v[52:53] op_sel_hi:[0,1]
	v_pk_fma_f32 v[156:157], v[184:185], v[48:49], v[156:157]
	v_cvt_pk_bf16_f32 v126, v126, v127
	v_pk_fma_f32 v[130:131], v[130:131], v[154:155], v[156:157]
	s_nop 0
	v_pk_mul_f32 v[154:155], v[130:131], v[130:131]
	s_nop 0
	v_pk_fma_f32 v[154:155], v[154:155], s[0:1], v[194:195] op_sel_hi:[1,0,0] neg_lo:[1,0,0] neg_hi:[1,0,0]
	s_nop 0
	v_pk_mul_f32 v[154:155], v[130:131], v[154:155]
	s_nop 0
	v_exp_f32_e32 v154, v154
	v_exp_f32_e32 v155, v155
	s_nop 0
	v_pk_add_f32 v[154:155], v[154:155], 1.0 op_sel_hi:[1,0]
	s_nop 0
	v_rcp_f32_e32 v154, v154
	v_rcp_f32_e32 v155, v155
	s_nop 0
	v_pk_mul_f32 v[130:131], v[130:131], v[154:155]
	s_nop 0
	v_pk_mul_f32 v[130:131], v[132:133], v[130:131]
	s_waitcnt lgkmcnt(1)
; __device__ __forceinline__ unsigned cvt_pk_bf16(float lo, float hi) { const f32x2_t v = {lo, hi}; return __builtin_bit_cast(unsigned, __builtin_convertvector(v, bf2_t)); }
; __device__ __forceinline__ float dpp_ror1(float v)  { return __builtin_bit_cast(float, __builtin_amdgcn_update_dpp(0, __builtin_bit_cast(int, v), 0x121, 0xf, 0xf, false)); }
; __device__ __forceinline__ float dpp_ror15(float v) { return __builtin_bit_cast(float, __builtin_amdgcn_update_dpp(0, __builtin_bit_cast(int, v), 0x12f, 0xf, 0xf, false)); }
;     __device__ __forceinline__ void operator()(const f32x4 (&acc_)[2][2][4][2], const Unit& u, int wr, int wc, int fr, int fq) const {
;     ...
;                         for (int k = 0; k < 2; ++k) { const int e = 2 * eh + k; const float g0 = acc[ai][0][m][n][e];
;                             const float pa = m > 0 ? dpp_ror1(acc[ai][0][m > 0 ? m - 1 : 0][n][e]) : bp[e];
;                             const float qa = m < 3 ? dpp_ror15(acc[ai][0][m < 3 ? m + 1 : 3][n][e]) : bn[e];
;                             gv[k] = g0; up[k] = acc[ai][1][m][n][e];
;                             p[k] = __builtin_bit_cast(float, __builtin_amdgcn_update_dpp(__builtin_bit_cast(int, pa), __builtin_bit_cast(int, g0), 0x111, 0xf, 0xf, false));
;                             q[k] = __builtin_bit_cast(float, __builtin_amdgcn_update_dpp(__builtin_bit_cast(int, qa), __builtin_bit_cast(int, g0), 0x101, 0xf, 0xf, false)); }
;                         const v2f a0 = (v2f){w0[2 * eh], w0[2 * eh + 1]} * mp, a1 = (v2f){w1[2 * eh], w1[2 * eh + 1]}, a2 = (v2f){w2[2 * eh], w2[2 * eh + 1]} * mn, ab = (v2f){bb[2 * eh], bb[2 * eh + 1]};
;                         const v2f x = a0 * p + (a1 * gv + (a2 * q + ab));
;                         const v2f arg = x * ((x * x) * (-0.10294324f) + (-2.3022082f));
;                         v2f ex; ex[0] = __builtin_amdgcn_exp2f(arg[0]); ex[1] = __builtin_amdgcn_exp2f(arg[1]);
;                         const v2f dn = ex + 1.0f; v2f rc; rc[0] = __builtin_amdgcn_rcpf(dn[0]); rc[1] = __builtin_amdgcn_rcpf(dn[1]);
;                         const v2f y = (x * rc) * up;
;                         ov[2 * n + eh] = cvt_pk_bf16(y[0], y[1]); }
;                 }
;                 if (lr >= 1 && lr <= 254 && t < Mtok) *(u32x4*)(ACT + (size_t)t * dff + j) = ov;
	v_pk_mul_f32 v[132:133], v[190:191], v[70:71] op_sel_hi:[0,1]
	s_waitcnt lgkmcnt(0)
	v_pk_fma_f32 v[132:133], v[132:133], v[152:153], v[66:67]
	v_cvt_pk_bf16_f32 v127, v130, v131
	v_pk_mul_f32 v[130:131], v[188:189], v[74:75] op_sel_hi:[0,1]
	v_pk_fma_f32 v[132:133], v[148:149], v[62:63], v[132:133]
	s_nop 0
	v_pk_fma_f32 v[130:131], v[130:131], v[150:151], v[132:133]
	s_nop 0
	v_pk_mul_f32 v[132:133], v[130:131], v[130:131]
	s_nop 0
	v_pk_fma_f32 v[132:133], v[132:133], s[0:1], v[194:195] op_sel_hi:[1,0,0] neg_lo:[1,0,0] neg_hi:[1,0,0]
	s_nop 0
	v_pk_mul_f32 v[132:133], v[130:131], v[132:133]
	s_nop 0
	v_exp_f32_e32 v132, v132
	v_exp_f32_e32 v133, v133
	s_nop 0
	v_pk_add_f32 v[132:133], v[132:133], 1.0 op_sel_hi:[1,0]
	s_nop 0
	v_rcp_f32_e32 v132, v132
	v_rcp_f32_e32 v133, v133
	s_nop 0
	v_pk_mul_f32 v[130:131], v[130:131], v[132:133]
	v_pk_mul_f32 v[132:133], v[190:191], v[72:73] op_sel_hi:[0,1]
	v_pk_fma_f32 v[132:133], v[132:133], v[144:145], v[68:69]
	v_pk_mul_f32 v[128:129], v[128:129], v[130:131]
	v_pk_mul_f32 v[130:131], v[188:189], v[76:77] op_sel_hi:[0,1]
	v_pk_fma_f32 v[132:133], v[146:147], v[64:65], v[132:133]
	v_cvt_pk_bf16_f32 v128, v128, v129
	v_pk_fma_f32 v[130:131], v[130:131], v[142:143], v[132:133]
	s_nop 0
	v_pk_mul_f32 v[132:133], v[130:131], v[130:131]
	s_nop 0
	v_pk_fma_f32 v[132:133], v[132:133], s[0:1], v[194:195] op_sel_hi:[1,0,0] neg_lo:[1,0,0] neg_hi:[1,0,0]
	s_nop 0
	v_pk_mul_f32 v[132:133], v[130:131], v[132:133]
	s_nop 0
	v_exp_f32_e32 v132, v132
	v_exp_f32_e32 v133, v133
	s_nop 0
	v_pk_add_f32 v[132:133], v[132:133], 1.0 op_sel_hi:[1,0]
	s_nop 0
	v_rcp_f32_e32 v132, v132
	v_rcp_f32_e32 v133, v133
	s_nop 0
	v_pk_mul_f32 v[130:131], v[130:131], v[132:133]
	s_nop 0
	v_pk_mul_f32 v[130:131], v[160:161], v[130:131]
	s_nop 0
	v_cvt_pk_bf16_f32 v129, v130, v131
	v_mov_b64_e32 v[130:131], s[18:19]
	v_mad_i64_i32 v[130:131], s[0:1], v181, s27, v[130:131]
	v_lshl_add_u64 v[130:131], v[176:177], 1, v[130:131]
	global_store_dwordx4 v[130:131], v[126:129], off
.LBB0_665:
	s_or_b64 exec, exec, s[46:47]
	v_pk_mul_f32 v[124:125], v[124:125], v[178:179] op_sel_hi:[1,0]
	v_pk_mul_f32 v[122:123], v[122:123], v[178:179] op_sel_hi:[1,0]
	v_pk_mul_f32 v[120:121], v[120:121], v[178:179] op_sel_hi:[1,0]
	v_pk_mul_f32 v[118:119], v[118:119], v[178:179] op_sel_hi:[1,0]
	v_add_u32_e32 v154, s33, v222
	v_mov_b32_dpp v150, v186 row_ror:1 row_mask:0xf bank_mask:0xf
	v_mov_b32_dpp v152, v122 row_ror:15 row_mask:0xf bank_mask:0xf
	v_mov_b32_dpp v151, v187 row_ror:1 row_mask:0xf bank_mask:0xf
	v_mov_b32_dpp v153, v123 row_ror:15 row_mask:0xf bank_mask:0xf
	v_mov_b32_dpp v142, v184 row_ror:1 row_mask:0xf bank_mask:0xf
	v_mov_b32_dpp v144, v124 row_ror:15 row_mask:0xf bank_mask:0xf
	v_mov_b32_dpp v143, v185 row_ror:1 row_mask:0xf bank_mask:0xf
	v_mov_b32_dpp v145, v125 row_ror:15 row_mask:0xf bank_mask:0xf
	v_mov_b32_dpp v130, v148 row_ror:1 row_mask:0xf bank_mask:0xf
	v_mov_b32_dpp v132, v118 row_ror:15 row_mask:0xf bank_mask:0xf
	v_mov_b32_dpp v131, v149 row_ror:1 row_mask:0xf bank_mask:0xf
	v_mov_b32_dpp v133, v119 row_ror:15 row_mask:0xf bank_mask:0xf
	v_mov_b32_dpp v126, v146 row_ror:1 row_mask:0xf bank_mask:0xf
	v_mov_b32_dpp v128, v120 row_ror:15 row_mask:0xf bank_mask:0xf
	v_mov_b32_dpp v127, v147 row_ror:1 row_mask:0xf bank_mask:0xf
	v_mov_b32_dpp v129, v121 row_ror:15 row_mask:0xf bank_mask:0xf
	v_cmp_gt_i32_e32 vcc, s26, v154
	v_mov_b32_dpp v150, v138 row_shr:1 row_mask:0xf bank_mask:0xf
	v_mov_b32_dpp v152, v138 row_shl:1 row_mask:0xf bank_mask:0xf
	v_mov_b32_dpp v151, v139 row_shr:1 row_mask:0xf bank_mask:0xf
	v_mov_b32_dpp v153, v139 row_shl:1 row_mask:0xf bank_mask:0xf
	v_mov_b32_dpp v142, v140 row_shr:1 row_mask:0xf bank_mask:0xf
	v_mov_b32_dpp v144, v140 row_shl:1 row_mask:0xf bank_mask:0xf
	v_mov_b32_dpp v143, v141 row_shr:1 row_mask:0xf bank_mask:0xf
	v_mov_b32_dpp v145, v141 row_shl:1 row_mask:0xf bank_mask:0xf
	v_mov_b32_dpp v130, v134 row_shr:1 row_mask:0xf bank_mask:0xf
	v_mov_b32_dpp v132, v134 row_shl:1 row_mask:0xf bank_mask:0xf
	v_mov_b32_dpp v131, v135 row_shr:1 row_mask:0xf bank_mask:0xf
	v_mov_b32_dpp v133, v135 row_shl:1 row_mask:0xf bank_mask:0xf
	v_mov_b32_dpp v126, v136 row_shr:1 row_mask:0xf bank_mask:0xf
	v_mov_b32_dpp v128, v136 row_shl:1 row_mask:0xf bank_mask:0xf
	v_mov_b32_dpp v127, v137 row_shr:1 row_mask:0xf bank_mask:0xf
	v_mov_b32_dpp v129, v137 row_shl:1 row_mask:0xf bank_mask:0xf
	s_and_b64 s[0:1], s[10:11], vcc
	s_and_saveexec_b64 s[46:47], s[0:1]
	s_cbranch_execz .LBB0_667
; __device__ __forceinline__ unsigned cvt_pk_bf16(float lo, float hi) { const f32x2_t v = {lo, hi}; return __builtin_bit_cast(unsigned, __builtin_convertvector(v, bf2_t)); }
; __device__ __forceinline__ float dpp_ror1(float v)  { return __builtin_bit_cast(float, __builtin_amdgcn_update_dpp(0, __builtin_bit_cast(int, v), 0x121, 0xf, 0xf, false)); }
; __device__ __forceinline__ float dpp_ror15(float v) { return __builtin_bit_cast(float, __builtin_amdgcn_update_dpp(0, __builtin_bit_cast(int, v), 0x12f, 0xf, 0xf, false)); }
;     __device__ __forceinline__ void operator()(const f32x4 (&acc_)[2][2][4][2], const Unit& u, int wr, int wc, int fr, int fq) const {
;     ...
;                         for (int k = 0; k < 2; ++k) { const int e = 2 * eh + k; const float g0 = acc[ai][0][m][n][e];
;                             const float pa = m > 0 ? dpp_ror1(acc[ai][0][m > 0 ? m - 1 : 0][n][e]) : bp[e];
;                             const float qa = m < 3 ? dpp_ror15(acc[ai][0][m < 3 ? m + 1 : 3][n][e]) : bn[e];
;                             gv[k] = g0; up[k] = acc[ai][1][m][n][e];
;                             p[k] = __builtin_bit_cast(float, __builtin_amdgcn_update_dpp(__builtin_bit_cast(int, pa), __builtin_bit_cast(int, g0), 0x111, 0xf, 0xf, false));
;                             q[k] = __builtin_bit_cast(float, __builtin_amdgcn_update_dpp(__builtin_bit_cast(int, qa), __builtin_bit_cast(int, g0), 0x101, 0xf, 0xf, false)); }
;                         const v2f a0 = (v2f){w0[2 * eh], w0[2 * eh + 1]} * mp, a1 = (v2f){w1[2 * eh], w1[2 * eh + 1]}, a2 = (v2f){w2[2 * eh], w2[2 * eh + 1]} * mn, ab = (v2f){bb[2 * eh], bb[2 * eh + 1]};
;                         const v2f x = a0 * p + (a1 * gv + (a2 * q + ab));
;                         const v2f arg = x * ((x * x) * (-0.10294324f) + (-2.3022082f));
;                         v2f ex; ex[0] = __builtin_amdgcn_exp2f(arg[0]); ex[1] = __builtin_amdgcn_exp2f(arg[1]);
;                         const v2f dn = ex + 1.0f; v2f rc; rc[0] = __builtin_amdgcn_rcpf(dn[0]); rc[1] = __builtin_amdgcn_rcpf(dn[1]);
;                         const v2f y = (x * rc) * up;
;                         ov[2 * n + eh] = cvt_pk_bf16(y[0], y[1]); }
;                 }
;                 if (lr >= 1 && lr <= 254 && t < Mtok) *(u32x4*)(ACT + (size_t)t * dff + j) = ov;
	v_and_b32_e32 v149, s34, v154
	v_cmp_eq_u32_e32 vcc, 0, v149
	v_mov_b32_e32 v183, v182
	v_mov_b32_e32 v146, v182
	v_cndmask_b32_e64 v148, 1.0, 0, vcc
	v_cmp_eq_u32_e32 vcc, s34, v149
	v_mov_b32_e32 v147, v182
	v_pk_mul_f32 v[116:117], v[116:117], v[146:147]
	v_cndmask_b32_e64 v156, 1.0, 0, vcc
	s_waitcnt lgkmcnt(5)
	v_pk_mul_f32 v[160:161], v[156:157], v[54:55] op_sel_hi:[0,1]
	s_waitcnt lgkmcnt(4)
	v_pk_fma_f32 v[152:153], v[160:161], v[152:153], v[58:59]
	v_pk_mul_f32 v[146:147], v[112:113], v[146:147]
	v_pk_mul_f32 v[112:113], v[110:111], v[182:183]
	v_pk_mul_f32 v[110:111], v[148:149], v[50:51] op_sel_hi:[0,1]
	v_pk_fma_f32 v[152:153], v[138:139], v[46:47], v[152:153]
	s_mov_b32 s0, 0xc0135761
	v_pk_fma_f32 v[110:111], v[110:111], v[150:151], v[152:153]
	v_mov_b64_e32 v[152:153], s[0:1]
	v_pk_mul_f32 v[150:151], v[110:111], v[110:111]
	s_mov_b32 s0, 0x3dd2d3e8
	v_pk_fma_f32 v[150:151], v[150:151], s[0:1], v[152:153] op_sel_hi:[1,0,0] neg_lo:[1,0,0] neg_hi:[1,0,0]
	v_pk_mul_f32 v[114:115], v[114:115], v[182:183]
	v_pk_mul_f32 v[150:151], v[110:111], v[150:151]
	s_nop 0
	v_exp_f32_e32 v150, v150
	v_exp_f32_e32 v151, v151
	s_nop 0
	v_pk_add_f32 v[150:151], v[150:151], 1.0 op_sel_hi:[1,0]
	s_nop 0
	v_rcp_f32_e32 v150, v150
	v_rcp_f32_e32 v151, v151
	s_nop 0
	v_pk_mul_f32 v[110:111], v[110:111], v[150:151]
	v_pk_mul_f32 v[150:151], v[156:157], v[56:57] op_sel_hi:[0,1]
	v_pk_fma_f32 v[144:145], v[150:151], v[144:145], v[60:61]
	v_pk_mul_f32 v[110:111], v[114:115], v[110:111]
	v_pk_mul_f32 v[114:115], v[148:149], v[52:53] op_sel_hi:[0,1]
	v_pk_fma_f32 v[144:145], v[140:141], v[48:49], v[144:145]
	v_cvt_pk_bf16_f32 v110, v110, v111
	v_pk_fma_f32 v[114:115], v[114:115], v[142:143], v[144:145]
	s_nop 0
	v_pk_mul_f32 v[142:143], v[114:115], v[114:115]
	s_nop 0
	v_pk_fma_f32 v[142:143], v[142:143], s[0:1], v[152:153] op_sel_hi:[1,0,0] neg_lo:[1,0,0] neg_hi:[1,0,0]
	s_nop 0
	v_pk_mul_f32 v[142:143], v[114:115], v[142:143]
	s_nop 0
	v_exp_f32_e32 v142, v142
	v_exp_f32_e32 v143, v143
	s_nop 0
	v_pk_add_f32 v[142:143], v[142:143], 1.0 op_sel_hi:[1,0]
	s_nop 0
	v_rcp_f32_e32 v142, v142
	v_rcp_f32_e32 v143, v143
	s_nop 0
	v_pk_mul_f32 v[114:115], v[114:115], v[142:143]
	s_nop 0
	v_pk_mul_f32 v[114:115], v[116:117], v[114:115]
	s_waitcnt lgkmcnt(1)
	v_pk_mul_f32 v[116:117], v[156:157], v[70:71] op_sel_hi:[0,1]
	s_waitcnt lgkmcnt(0)
	v_pk_fma_f32 v[116:117], v[116:117], v[132:133], v[66:67]
	v_cvt_pk_bf16_f32 v111, v114, v115
	v_pk_mul_f32 v[114:115], v[148:149], v[74:75] op_sel_hi:[0,1]
	v_pk_fma_f32 v[116:117], v[134:135], v[62:63], v[116:117]
	s_nop 0
	v_pk_fma_f32 v[114:115], v[114:115], v[130:131], v[116:117]
	s_nop 0
	v_pk_mul_f32 v[116:117], v[114:115], v[114:115]
	s_nop 0
	v_pk_fma_f32 v[116:117], v[116:117], s[0:1], v[152:153] op_sel_hi:[1,0,0] neg_lo:[1,0,0] neg_hi:[1,0,0]
	s_nop 0
	v_pk_mul_f32 v[116:117], v[114:115], v[116:117]
	s_nop 0
	v_exp_f32_e32 v116, v116
	v_exp_f32_e32 v117, v117
	s_nop 0
	v_pk_add_f32 v[116:117], v[116:117], 1.0 op_sel_hi:[1,0]
	s_nop 0
	v_rcp_f32_e32 v116, v116
	v_rcp_f32_e32 v117, v117
	s_nop 0
	v_pk_mul_f32 v[114:115], v[114:115], v[116:117]
	v_pk_mul_f32 v[116:117], v[156:157], v[72:73] op_sel_hi:[0,1]
	v_pk_fma_f32 v[116:117], v[116:117], v[128:129], v[68:69]
	v_pk_mul_f32 v[112:113], v[112:113], v[114:115]
	v_pk_mul_f32 v[114:115], v[148:149], v[76:77] op_sel_hi:[0,1]
	v_pk_fma_f32 v[116:117], v[136:137], v[64:65], v[116:117]
	v_cvt_pk_bf16_f32 v112, v112, v113
	v_pk_fma_f32 v[114:115], v[114:115], v[126:127], v[116:117]
	s_nop 0
	v_pk_mul_f32 v[116:117], v[114:115], v[114:115]
	s_nop 0
	v_pk_fma_f32 v[116:117], v[116:117], s[0:1], v[152:153] op_sel_hi:[1,0,0] neg_lo:[1,0,0] neg_hi:[1,0,0]
	s_nop 0
	v_pk_mul_f32 v[116:117], v[114:115], v[116:117]
	s_nop 0
	v_exp_f32_e32 v116, v116
	v_exp_f32_e32 v117, v117
	s_nop 0
	v_pk_add_f32 v[116:117], v[116:117], 1.0 op_sel_hi:[1,0]
	s_nop 0
	v_rcp_f32_e32 v116, v116
	v_rcp_f32_e32 v117, v117
	s_nop 0
	v_pk_mul_f32 v[114:115], v[114:115], v[116:117]
	s_nop 0
	v_pk_mul_f32 v[114:115], v[146:147], v[114:115]
	s_nop 0
	v_cvt_pk_bf16_f32 v113, v114, v115
	v_mov_b64_e32 v[114:115], s[18:19]
	v_mad_i64_i32 v[114:115], s[0:1], v154, s27, v[114:115]
	v_lshl_add_u64 v[114:115], v[176:177], 1, v[114:115]
	global_store_dwordx4 v[114:115], v[110:113], off
;     __device__ __forceinline__ void operator()(const f32x4 (&acc_)[2][2][4][2], const Unit& u, int wr, int wc, int fr, int fq) const {
;     ...
;                     const f32x4 w0 = *(const PG8_LAS f32x4*)(wl + jj + 4 * n), w1 = *(const PG8_LAS f32x4*)(wl + 128 + jj + 4 * n), w2 = *(const PG8_LAS f32x4*)(wl + 256 + jj + 4 * n), bb = *(const PG8_LAS f32x4*)(wl + 384 + jj + 4 * n);
;                     f32x4 bp = {0.f, 0.f, 0.f, 0.f}, bn = {0.f, 0.f, 0.f, 0.f};
;                     if (m == 0 && sp >= 0) bp = *(const PG8_LAS f32x4*)(xg + sp * 128 + jj + 4 * n) * xg[1536 + ai * HALF + wr * 64 - 1];
;                     if (m == 3 && sn >= 0) bn = *(const PG8_LAS f32x4*)(xg + sn * 128 + jj + 4 * n) * xg[1536 + ai * HALF + wr * 64 + 64];
; #pragma unroll
;                     for (int eh = 0; eh < 2; ++eh) { v2f gv, p, q, up;
; #pragma unroll
;                         for (int k = 0; k < 2; ++k) { const int e = 2 * eh + k; const float g0 = acc[ai][0][m][n][e];
;                             const float pa = m > 0 ? dpp_ror1(acc[ai][0][m > 0 ? m - 1 : 0][n][e]) : bp[e];
;                             const float qa = m < 3 ? dpp_ror15(acc[ai][0][m < 3 ? m + 1 : 3][n][e]) : bn[e];
;                             gv[k] = g0; up[k] = acc[ai][1][m][n][e];
;                             p[k] = __builtin_bit_cast(float, __builtin_amdgcn_update_dpp(__builtin_bit_cast(int, pa), __builtin_bit_cast(int, g0), 0x111, 0xf, 0xf, false));
;                             q[k] = __builtin_bit_cast(float, __builtin_amdgcn_update_dpp(__builtin_bit_cast(int, qa), __builtin_bit_cast(int, g0), 0x101, 0xf, 0xf, false)); }
;                         const v2f a0 = (v2f){w0[2 * eh], w0[2 * eh + 1]} * mp, a1 = (v2f){w1[2 * eh], w1[2 * eh + 1]}, a2 = (v2f){w2[2 * eh], w2[2 * eh + 1]} * mn, ab = (v2f){bb[2 * eh], bb[2 * eh + 1]};
;                         const v2f x = a0 * p + (a1 * gv + (a2 * q + ab));
;                         const v2f arg = x * ((x * x) * (-0.10294324f) + (-2.3022082f));
;                         v2f ex; ex[0] = __builtin_amdgcn_exp2f(arg[0]); ex[1] = __builtin_amdgcn_exp2f(arg[1]);
;                         const v2f dn = ex + 1.0f; v2f rc; rc[0] = __builtin_amdgcn_rcpf(dn[0]); rc[1] = __builtin_amdgcn_rcpf(dn[1]);
;                         const v2f y = (x * rc) * up;
;                         ov[2 * n + eh] = cvt_pk_bf16(y[0], y[1]); }
;                 }
.LBB0_667:
	s_or_b64 exec, exec, s[46:47]
	v_mov_b32_e32 v114, s79
	ds_read_b128 v[110:113], v240
	ds_read_b32 v144, v114 offset:6400
	ds_read_b128 v[114:117], v240 offset:16
	v_add_u32_e32 v142, s33, v223
	s_waitcnt lgkmcnt(1)
	v_pk_mul_f32 v[126:127], v[112:113], v[144:145] op_sel_hi:[1,0]
	v_pk_mul_f32 v[132:133], v[110:111], v[144:145] op_sel_hi:[1,0]
	s_waitcnt lgkmcnt(0)
	v_pk_mul_f32 v[110:111], v[144:145], v[116:117] op_sel_hi:[0,1]
	v_pk_mul_f32 v[116:117], v[144:145], v[114:115] op_sel_hi:[0,1]
	v_mov_b32_dpp v130, v138 row_ror:1 row_mask:0xf bank_mask:0xf
	v_mov_b32_dpp v131, v139 row_ror:1 row_mask:0xf bank_mask:0xf
	v_mov_b32_dpp v128, v140 row_ror:1 row_mask:0xf bank_mask:0xf
	v_mov_b32_dpp v129, v141 row_ror:1 row_mask:0xf bank_mask:0xf
	v_mov_b32_dpp v114, v134 row_ror:1 row_mask:0xf bank_mask:0xf
	v_mov_b32_dpp v115, v135 row_ror:1 row_mask:0xf bank_mask:0xf
	v_mov_b32_dpp v112, v136 row_ror:1 row_mask:0xf bank_mask:0xf
	v_mov_b32_dpp v113, v137 row_ror:1 row_mask:0xf bank_mask:0xf
	v_cmp_gt_i32_e32 vcc, s26, v142
	v_mov_b32_dpp v130, v122 row_shr:1 row_mask:0xf bank_mask:0xf
	v_mov_b32_dpp v132, v122 row_shl:1 row_mask:0xf bank_mask:0xf
	v_mov_b32_dpp v131, v123 row_shr:1 row_mask:0xf bank_mask:0xf
	v_mov_b32_dpp v133, v123 row_shl:1 row_mask:0xf bank_mask:0xf
	v_mov_b32_dpp v128, v124 row_shr:1 row_mask:0xf bank_mask:0xf
	v_mov_b32_dpp v126, v124 row_shl:1 row_mask:0xf bank_mask:0xf
	v_mov_b32_dpp v129, v125 row_shr:1 row_mask:0xf bank_mask:0xf
	v_mov_b32_dpp v127, v125 row_shl:1 row_mask:0xf bank_mask:0xf
	v_mov_b32_dpp v114, v118 row_shr:1 row_mask:0xf bank_mask:0xf
	v_mov_b32_dpp v116, v118 row_shl:1 row_mask:0xf bank_mask:0xf
	v_mov_b32_dpp v115, v119 row_shr:1 row_mask:0xf bank_mask:0xf
	v_mov_b32_dpp v117, v119 row_shl:1 row_mask:0xf bank_mask:0xf
	v_mov_b32_dpp v112, v120 row_shr:1 row_mask:0xf bank_mask:0xf
	v_mov_b32_dpp v110, v120 row_shl:1 row_mask:0xf bank_mask:0xf
	v_mov_b32_dpp v113, v121 row_shr:1 row_mask:0xf bank_mask:0xf
	v_mov_b32_dpp v111, v121 row_shl:1 row_mask:0xf bank_mask:0xf
	s_and_b64 s[0:1], s[12:13], vcc
	s_and_saveexec_b64 s[46:47], s[0:1]
	s_cbranch_execz .LBB0_669
	v_mov_b32_e32 v134, v178
	v_mov_b32_e32 v135, v178
	v_mov_b32_e32 v136, v178
	v_mov_b32_e32 v137, v178
	v_pk_mul_f32 v[108:109], v[108:109], v[136:137]
	v_pk_mul_f32 v[106:107], v[106:107], v[134:135]
	v_pk_mul_f32 v[136:137], v[104:105], v[136:137]
	v_pk_mul_f32 v[104:105], v[102:103], v[134:135]
	v_and_b32_e32 v135, s34, v142
	v_cmp_eq_u32_e32 vcc, 0, v135
	s_mov_b32 s0, 0xc0135761
	s_nop 0
	v_cndmask_b32_e64 v134, 1.0, 0, vcc
	v_cmp_eq_u32_e32 vcc, s34, v135
	v_pk_mul_f32 v[102:103], v[134:135], v[50:51] op_sel_hi:[0,1]
	s_nop 0
	v_cndmask_b32_e64 v138, 1.0, 0, vcc
	v_pk_mul_f32 v[140:141], v[138:139], v[54:55] op_sel_hi:[0,1]
	v_pk_fma_f32 v[132:133], v[140:141], v[132:133], v[58:59]
	v_pk_mul_f32 v[140:141], v[138:139], v[56:57] op_sel_hi:[0,1]
	v_pk_fma_f32 v[122:123], v[122:123], v[46:47], v[132:133]
	v_pk_fma_f32 v[126:127], v[140:141], v[126:127], v[60:61]
	v_pk_fma_f32 v[102:103], v[102:103], v[130:131], v[122:123]
	v_pk_mul_f32 v[132:133], v[134:135], v[52:53] op_sel_hi:[0,1]
	v_pk_fma_f32 v[124:125], v[124:125], v[48:49], v[126:127]
	v_pk_mul_f32 v[122:123], v[102:103], v[102:103]
	v_mov_b64_e32 v[130:131], s[0:1]
	s_mov_b32 s0, 0x3dd2d3e8
	v_pk_fma_f32 v[124:125], v[132:133], v[128:129], v[124:125]
	v_pk_fma_f32 v[122:123], v[122:123], s[0:1], v[130:131] op_sel_hi:[1,0,0] neg_lo:[1,0,0] neg_hi:[1,0,0]
	v_pk_mul_f32 v[126:127], v[124:125], v[124:125]
	v_pk_mul_f32 v[122:123], v[102:103], v[122:123]
	v_pk_fma_f32 v[126:127], v[126:127], s[0:1], v[130:131] op_sel_hi:[1,0,0] neg_lo:[1,0,0] neg_hi:[1,0,0]
	v_exp_f32_e32 v122, v122
	v_exp_f32_e32 v123, v123
	v_pk_mul_f32 v[126:127], v[124:125], v[126:127]
	v_pk_add_f32 v[122:123], v[122:123], 1.0 op_sel_hi:[1,0]
	v_exp_f32_e32 v126, v126
	v_exp_f32_e32 v127, v127
	v_rcp_f32_e32 v122, v122
	v_rcp_f32_e32 v123, v123
	v_pk_add_f32 v[126:127], v[126:127], 1.0 op_sel_hi:[1,0]
	s_nop 0
	v_rcp_f32_e32 v126, v126
	v_rcp_f32_e32 v127, v127
	v_pk_mul_f32 v[102:103], v[102:103], v[122:123]
	s_nop 0
	v_pk_mul_f32 v[102:103], v[106:107], v[102:103]
	v_pk_mul_f32 v[106:107], v[124:125], v[126:127]
	v_cvt_pk_bf16_f32 v102, v102, v103
	v_pk_mul_f32 v[106:107], v[108:109], v[106:107]
	v_pk_mul_f32 v[108:109], v[138:139], v[70:71] op_sel_hi:[0,1]
	v_pk_fma_f32 v[108:109], v[108:109], v[116:117], v[66:67]
	v_pk_mul_f32 v[116:117], v[138:139], v[72:73] op_sel_hi:[0,1]
	v_cvt_pk_bf16_f32 v103, v106, v107
	v_pk_mul_f32 v[106:107], v[134:135], v[74:75] op_sel_hi:[0,1]
	v_pk_fma_f32 v[108:109], v[118:119], v[62:63], v[108:109]
	v_pk_fma_f32 v[110:111], v[116:117], v[110:111], v[68:69]
	v_pk_fma_f32 v[106:107], v[106:107], v[114:115], v[108:109]
	v_pk_mul_f32 v[114:115], v[134:135], v[76:77] op_sel_hi:[0,1]
	v_pk_fma_f32 v[110:111], v[120:121], v[64:65], v[110:111]
	v_pk_mul_f32 v[108:109], v[106:107], v[106:107]
	v_pk_fma_f32 v[110:111], v[114:115], v[112:113], v[110:111]
	v_pk_fma_f32 v[108:109], v[108:109], s[0:1], v[130:131] op_sel_hi:[1,0,0] neg_lo:[1,0,0] neg_hi:[1,0,0]
	v_pk_mul_f32 v[112:113], v[110:111], v[110:111]
	v_pk_mul_f32 v[108:109], v[106:107], v[108:109]
	v_pk_fma_f32 v[112:113], v[112:113], s[0:1], v[130:131] op_sel_hi:[1,0,0] neg_lo:[1,0,0] neg_hi:[1,0,0]
	v_exp_f32_e32 v108, v108
	v_exp_f32_e32 v109, v109
	v_pk_mul_f32 v[112:113], v[110:111], v[112:113]
	v_pk_add_f32 v[108:109], v[108:109], 1.0 op_sel_hi:[1,0]
	v_exp_f32_e32 v112, v112
	v_exp_f32_e32 v113, v113
	v_rcp_f32_e32 v108, v108
	v_rcp_f32_e32 v109, v109
	v_pk_add_f32 v[112:113], v[112:113], 1.0 op_sel_hi:[1,0]
	s_nop 0
	v_rcp_f32_e32 v112, v112
	v_rcp_f32_e32 v113, v113
	v_pk_mul_f32 v[106:107], v[106:107], v[108:109]
	s_nop 0
	v_pk_mul_f32 v[104:105], v[104:105], v[106:107]
	v_pk_mul_f32 v[106:107], v[110:111], v[112:113]
	v_cvt_pk_bf16_f32 v104, v104, v105
	v_pk_mul_f32 v[106:107], v[136:137], v[106:107]
	s_nop 0
	v_cvt_pk_bf16_f32 v105, v106, v107
	v_mov_b64_e32 v[106:107], s[18:19]
	v_mad_i64_i32 v[106:107], s[0:1], v142, s27, v[106:107]
	v_lshl_add_u64 v[106:107], v[176:177], 1, v[106:107]
	global_store_dwordx4 v[106:107], v[102:105], off
;     __device__ __forceinline__ void operator()(const f32x4 (&acc_)[2][2][4][2], const Unit& u, int wr, int wc, int fr, int fq) const {
;     ...
;                     const f32x4 w0 = *(const PG8_LAS f32x4*)(wl + jj + 4 * n), w1 = *(const PG8_LAS f32x4*)(wl + 128 + jj + 4 * n), w2 = *(const PG8_LAS f32x4*)(wl + 256 + jj + 4 * n), bb = *(const PG8_LAS f32x4*)(wl + 384 + jj + 4 * n);
;                     f32x4 bp = {0.f, 0.f, 0.f, 0.f}, bn = {0.f, 0.f, 0.f, 0.f};
;                     if (m == 0 && sp >= 0) bp = *(const PG8_LAS f32x4*)(xg + sp * 128 + jj + 4 * n) * xg[1536 + ai * HALF + wr * 64 - 1];
;                     if (m == 3 && sn >= 0) bn = *(const PG8_LAS f32x4*)(xg + sn * 128 + jj + 4 * n) * xg[1536 + ai * HALF + wr * 64 + 64];
; #pragma unroll
;                     for (int eh = 0; eh < 2; ++eh) { v2f gv, p, q, up;
; #pragma unroll
;                         for (int k = 0; k < 2; ++k) { const int e = 2 * eh + k; const float g0 = acc[ai][0][m][n][e];
;                             const float pa = m > 0 ? dpp_ror1(acc[ai][0][m > 0 ? m - 1 : 0][n][e]) : bp[e];
;                             const float qa = m < 3 ? dpp_ror15(acc[ai][0][m < 3 ? m + 1 : 3][n][e]) : bn[e];
;                             gv[k] = g0; up[k] = acc[ai][1][m][n][e];
;                             p[k] = __builtin_bit_cast(float, __builtin_amdgcn_update_dpp(__builtin_bit_cast(int, pa), __builtin_bit_cast(int, g0), 0x111, 0xf, 0xf, false));
;                             q[k] = __builtin_bit_cast(float, __builtin_amdgcn_update_dpp(__builtin_bit_cast(int, qa), __builtin_bit_cast(int, g0), 0x101, 0xf, 0xf, false)); }
;                         const v2f a0 = (v2f){w0[2 * eh], w0[2 * eh + 1]} * mp, a1 = (v2f){w1[2 * eh], w1[2 * eh + 1]}, a2 = (v2f){w2[2 * eh], w2[2 * eh + 1]} * mn, ab = (v2f){bb[2 * eh], bb[2 * eh + 1]};
;                         const v2f x = a0 * p + (a1 * gv + (a2 * q + ab));
;                         const v2f arg = x * ((x * x) * (-0.10294324f) + (-2.3022082f));
;                         v2f ex; ex[0] = __builtin_amdgcn_exp2f(arg[0]); ex[1] = __builtin_amdgcn_exp2f(arg[1]);
;                         const v2f dn = ex + 1.0f; v2f rc; rc[0] = __builtin_amdgcn_rcpf(dn[0]); rc[1] = __builtin_amdgcn_rcpf(dn[1]);
;                         const v2f y = (x * rc) * up;
;                         ov[2 * n + eh] = cvt_pk_bf16(y[0], y[1]); }
;                 }
.LBB0_669:
	s_or_b64 exec, exec, s[46:47]
	s_nop 0
	v_pk_mul_f32 v[102:103], v[88:89], v[180:181] op_sel_hi:[1,0]
	v_pk_mul_f32 v[104:105], v[86:87], v[180:181] op_sel_hi:[1,0]
	v_mov_b32_e32 v88, v179
	v_mov_b32_e32 v86, s79
	v_pk_mul_f32 v[106:107], v[92:93], v[180:181] op_sel_hi:[1,0]
	v_pk_mul_f32 v[108:109], v[90:91], v[180:181] op_sel_hi:[1,0]
	v_pk_mul_f32 v[90:91], v[100:101], v[88:89] op_sel_hi:[1,0]
	v_pk_mul_f32 v[92:93], v[98:99], v[88:89] op_sel_hi:[1,0]
	ds_read_b128 v[98:101], v241
	ds_read_b32 v124, v86 offset:6652
	ds_read_b128 v[120:123], v241 offset:16
	v_pk_mul_f32 v[86:87], v[96:97], v[88:89] op_sel_hi:[1,0]
	v_pk_mul_f32 v[88:89], v[94:95], v[88:89] op_sel_hi:[1,0]
	v_add_u32_e32 v118, s33, v224
	s_waitcnt lgkmcnt(1)
	v_pk_mul_f32 v[110:111], v[100:101], v[124:125] op_sel_hi:[1,0]
	v_pk_mul_f32 v[114:115], v[98:99], v[124:125] op_sel_hi:[1,0]
	v_mov_b32_dpp v116, v92 row_ror:15 row_mask:0xf bank_mask:0xf
	v_mov_b32_dpp v117, v93 row_ror:15 row_mask:0xf bank_mask:0xf
	v_mov_b32_dpp v112, v90 row_ror:15 row_mask:0xf bank_mask:0xf
	v_mov_b32_dpp v113, v91 row_ror:15 row_mask:0xf bank_mask:0xf
	s_waitcnt lgkmcnt(0)
	v_pk_mul_f32 v[94:95], v[124:125], v[122:123] op_sel_hi:[0,1]
	v_pk_mul_f32 v[98:99], v[124:125], v[120:121] op_sel_hi:[0,1]
	v_mov_b32_dpp v100, v88 row_ror:15 row_mask:0xf bank_mask:0xf
	v_mov_b32_dpp v101, v89 row_ror:15 row_mask:0xf bank_mask:0xf
	v_mov_b32_dpp v96, v86 row_ror:15 row_mask:0xf bank_mask:0xf
	v_mov_b32_dpp v97, v87 row_ror:15 row_mask:0xf bank_mask:0xf
	v_cmp_gt_i32_e32 vcc, s26, v118
	v_mov_b32_dpp v114, v108 row_shr:1 row_mask:0xf bank_mask:0xf
	v_mov_b32_dpp v116, v108 row_shl:1 row_mask:0xf bank_mask:0xf
	v_mov_b32_dpp v115, v109 row_shr:1 row_mask:0xf bank_mask:0xf
	v_mov_b32_dpp v117, v109 row_shl:1 row_mask:0xf bank_mask:0xf
	v_mov_b32_dpp v110, v106 row_shr:1 row_mask:0xf bank_mask:0xf
	v_mov_b32_dpp v112, v106 row_shl:1 row_mask:0xf bank_mask:0xf
	v_mov_b32_dpp v111, v107 row_shr:1 row_mask:0xf bank_mask:0xf
	v_mov_b32_dpp v113, v107 row_shl:1 row_mask:0xf bank_mask:0xf
	v_mov_b32_dpp v98, v104 row_shr:1 row_mask:0xf bank_mask:0xf
	v_mov_b32_dpp v100, v104 row_shl:1 row_mask:0xf bank_mask:0xf
	v_mov_b32_dpp v99, v105 row_shr:1 row_mask:0xf bank_mask:0xf
	v_mov_b32_dpp v101, v105 row_shl:1 row_mask:0xf bank_mask:0xf
	v_mov_b32_dpp v94, v102 row_shr:1 row_mask:0xf bank_mask:0xf
	v_mov_b32_dpp v96, v102 row_shl:1 row_mask:0xf bank_mask:0xf
	v_mov_b32_dpp v95, v103 row_shr:1 row_mask:0xf bank_mask:0xf
	v_mov_b32_dpp v97, v103 row_shl:1 row_mask:0xf bank_mask:0xf
	s_and_b64 s[0:1], s[14:15], vcc
	s_and_saveexec_b64 s[46:47], s[0:1]
	s_cbranch_execz .LBB0_671
	v_and_b32_e32 v119, s34, v118
	v_cmp_eq_u32_e32 vcc, 0, v119
	v_mov_b32_e32 v181, v180
	v_mov_b32_e32 v120, v180
	v_cndmask_b32_e64 v122, 1.0, 0, vcc
	v_cmp_eq_u32_e32 vcc, s34, v119
	v_mov_b32_e32 v121, v180
	v_pk_mul_f32 v[84:85], v[84:85], v[120:121]
	v_cndmask_b32_e64 v124, 1.0, 0, vcc
	v_pk_mul_f32 v[126:127], v[124:125], v[54:55] op_sel_hi:[0,1]
	v_pk_fma_f32 v[116:117], v[126:127], v[116:117], v[58:59]
	v_pk_mul_f32 v[120:121], v[80:81], v[120:121]
	v_pk_mul_f32 v[80:81], v[78:79], v[180:181]
	v_pk_mul_f32 v[78:79], v[122:123], v[50:51] op_sel_hi:[0,1]
	v_pk_fma_f32 v[116:117], v[108:109], v[46:47], v[116:117]
	s_mov_b32 s0, 0xc0135761
	v_pk_fma_f32 v[78:79], v[78:79], v[114:115], v[116:117]
	v_mov_b64_e32 v[116:117], s[0:1]
	v_pk_mul_f32 v[114:115], v[78:79], v[78:79]
	s_mov_b32 s0, 0x3dd2d3e8
	v_pk_fma_f32 v[114:115], v[114:115], s[0:1], v[116:117] op_sel_hi:[1,0,0] neg_lo:[1,0,0] neg_hi:[1,0,0]
	v_pk_mul_f32 v[82:83], v[82:83], v[180:181]
	v_pk_mul_f32 v[114:115], v[78:79], v[114:115]
	s_nop 0
	v_exp_f32_e32 v114, v114
	v_exp_f32_e32 v115, v115
	s_nop 0
	v_pk_add_f32 v[114:115], v[114:115], 1.0 op_sel_hi:[1,0]
	s_nop 0
	v_rcp_f32_e32 v114, v114
	v_rcp_f32_e32 v115, v115
	s_nop 0
	v_pk_mul_f32 v[78:79], v[78:79], v[114:115]
	v_pk_mul_f32 v[114:115], v[124:125], v[56:57] op_sel_hi:[0,1]
	v_pk_fma_f32 v[112:113], v[114:115], v[112:113], v[60:61]
	v_pk_mul_f32 v[78:79], v[82:83], v[78:79]
	v_pk_mul_f32 v[82:83], v[122:123], v[52:53] op_sel_hi:[0,1]
	v_pk_fma_f32 v[112:113], v[106:107], v[48:49], v[112:113]
	v_cvt_pk_bf16_f32 v78, v78, v79
	v_pk_fma_f32 v[82:83], v[82:83], v[110:111], v[112:113]
	s_nop 0
	v_pk_mul_f32 v[110:111], v[82:83], v[82:83]
	s_nop 0
	v_pk_fma_f32 v[110:111], v[110:111], s[0:1], v[116:117] op_sel_hi:[1,0,0] neg_lo:[1,0,0] neg_hi:[1,0,0]
	s_nop 0
	v_pk_mul_f32 v[110:111], v[82:83], v[110:111]
	s_nop 0
	v_exp_f32_e32 v110, v110
	v_exp_f32_e32 v111, v111
	s_nop 0
	v_pk_add_f32 v[110:111], v[110:111], 1.0 op_sel_hi:[1,0]
	s_nop 0
	v_rcp_f32_e32 v110, v110
	v_rcp_f32_e32 v111, v111
	s_nop 0
	v_pk_mul_f32 v[82:83], v[82:83], v[110:111]
	s_nop 0
	v_pk_mul_f32 v[82:83], v[84:85], v[82:83]
	v_pk_mul_f32 v[84:85], v[124:125], v[70:71] op_sel_hi:[0,1]
	v_pk_fma_f32 v[84:85], v[84:85], v[100:101], v[66:67]
	v_cvt_pk_bf16_f32 v79, v82, v83
	v_pk_mul_f32 v[82:83], v[122:123], v[74:75] op_sel_hi:[0,1]
	v_pk_fma_f32 v[84:85], v[104:105], v[62:63], v[84:85]
	s_nop 0
	v_pk_fma_f32 v[82:83], v[82:83], v[98:99], v[84:85]
	s_nop 0
	v_pk_mul_f32 v[84:85], v[82:83], v[82:83]
	s_nop 0
	v_pk_fma_f32 v[84:85], v[84:85], s[0:1], v[116:117] op_sel_hi:[1,0,0] neg_lo:[1,0,0] neg_hi:[1,0,0]
	s_nop 0
	v_pk_mul_f32 v[84:85], v[82:83], v[84:85]
	s_nop 0
	v_exp_f32_e32 v84, v84
	v_exp_f32_e32 v85, v85
	s_nop 0
	v_pk_add_f32 v[84:85], v[84:85], 1.0 op_sel_hi:[1,0]
	s_nop 0
	v_rcp_f32_e32 v84, v84
	v_rcp_f32_e32 v85, v85
	s_nop 0
	v_pk_mul_f32 v[82:83], v[82:83], v[84:85]
	v_pk_mul_f32 v[84:85], v[124:125], v[72:73] op_sel_hi:[0,1]
	v_pk_fma_f32 v[84:85], v[84:85], v[96:97], v[68:69]
	v_pk_mul_f32 v[80:81], v[80:81], v[82:83]
	v_pk_mul_f32 v[82:83], v[122:123], v[76:77] op_sel_hi:[0,1]
	v_pk_fma_f32 v[84:85], v[102:103], v[64:65], v[84:85]
	v_cvt_pk_bf16_f32 v80, v80, v81
	v_pk_fma_f32 v[82:83], v[82:83], v[94:95], v[84:85]
	s_nop 0
	v_pk_mul_f32 v[84:85], v[82:83], v[82:83]
	s_nop 0
	v_pk_fma_f32 v[84:85], v[84:85], s[0:1], v[116:117] op_sel_hi:[1,0,0] neg_lo:[1,0,0] neg_hi:[1,0,0]
	s_nop 0
	v_pk_mul_f32 v[84:85], v[82:83], v[84:85]
	s_nop 0
	v_exp_f32_e32 v84, v84
	v_exp_f32_e32 v85, v85
	s_nop 0
	v_pk_add_f32 v[84:85], v[84:85], 1.0 op_sel_hi:[1,0]
	s_nop 0
	v_rcp_f32_e32 v84, v84
	v_rcp_f32_e32 v85, v85
	s_nop 0
	v_pk_mul_f32 v[82:83], v[82:83], v[84:85]
	s_nop 0
	v_pk_mul_f32 v[82:83], v[120:121], v[82:83]
	s_nop 0
	v_cvt_pk_bf16_f32 v81, v82, v83
	v_mov_b64_e32 v[82:83], s[18:19]
	v_mad_i64_i32 v[82:83], s[0:1], v118, s27, v[82:83]
	v_lshl_add_u64 v[82:83], v[176:177], 1, v[82:83]
	global_store_dwordx4 v[82:83], v[78:81], off
;     __device__ __forceinline__ void operator()(const f32x4 (&acc_)[2][2][4][2], const Unit& u, int wr, int wc, int fr, int fq) const {
;     ...
;                     const f32x4 w0 = *(const PG8_LAS f32x4*)(wl + jj + 4 * n), w1 = *(const PG8_LAS f32x4*)(wl + 128 + jj + 4 * n), w2 = *(const PG8_LAS f32x4*)(wl + 256 + jj + 4 * n), bb = *(const PG8_LAS f32x4*)(wl + 384 + jj + 4 * n);
;                     f32x4 bp = {0.f, 0.f, 0.f, 0.f}, bn = {0.f, 0.f, 0.f, 0.f};
;                     if (m == 0 && sp >= 0) bp = *(const PG8_LAS f32x4*)(xg + sp * 128 + jj + 4 * n) * xg[1536 + ai * HALF + wr * 64 - 1];
;                     if (m == 3 && sn >= 0) bn = *(const PG8_LAS f32x4*)(xg + sn * 128 + jj + 4 * n) * xg[1536 + ai * HALF + wr * 64 + 64];
; #pragma unroll
;                     for (int eh = 0; eh < 2; ++eh) { v2f gv, p, q, up;
; #pragma unroll
;                         for (int k = 0; k < 2; ++k) { const int e = 2 * eh + k; const float g0 = acc[ai][0][m][n][e];
;                             const float pa = m > 0 ? dpp_ror1(acc[ai][0][m > 0 ? m - 1 : 0][n][e]) : bp[e];
;                             const float qa = m < 3 ? dpp_ror15(acc[ai][0][m < 3 ? m + 1 : 3][n][e]) : bn[e];
;                             gv[k] = g0; up[k] = acc[ai][1][m][n][e];
;                             p[k] = __builtin_bit_cast(float, __builtin_amdgcn_update_dpp(__builtin_bit_cast(int, pa), __builtin_bit_cast(int, g0), 0x111, 0xf, 0xf, false));
;                             q[k] = __builtin_bit_cast(float, __builtin_amdgcn_update_dpp(__builtin_bit_cast(int, qa), __builtin_bit_cast(int, g0), 0x101, 0xf, 0xf, false)); }
;                         const v2f a0 = (v2f){w0[2 * eh], w0[2 * eh + 1]} * mp, a1 = (v2f){w1[2 * eh], w1[2 * eh + 1]}, a2 = (v2f){w2[2 * eh], w2[2 * eh + 1]} * mn, ab = (v2f){bb[2 * eh], bb[2 * eh + 1]};
;                         const v2f x = a0 * p + (a1 * gv + (a2 * q + ab));
;                         const v2f arg = x * ((x * x) * (-0.10294324f) + (-2.3022082f));
;                         v2f ex; ex[0] = __builtin_amdgcn_exp2f(arg[0]); ex[1] = __builtin_amdgcn_exp2f(arg[1]);
;                         const v2f dn = ex + 1.0f; v2f rc; rc[0] = __builtin_amdgcn_rcpf(dn[0]); rc[1] = __builtin_amdgcn_rcpf(dn[1]);
;                         const v2f y = (x * rc) * up;
;                         ov[2 * n + eh] = cvt_pk_bf16(y[0], y[1]); }
;                 }
.LBB0_671:
	s_or_b64 exec, exec, s[46:47]
	v_pk_mul_f32 v[44:45], v[44:45], v[174:175] op_sel_hi:[1,0]
	v_pk_mul_f32 v[42:43], v[42:43], v[174:175] op_sel_hi:[1,0]
	v_pk_mul_f32 v[40:41], v[40:41], v[174:175] op_sel_hi:[1,0]
	v_pk_mul_f32 v[38:39], v[38:39], v[174:175] op_sel_hi:[1,0]
	v_add_u32_e32 v110, s33, v225
	v_mov_b32_dpp v98, v108 row_ror:1 row_mask:0xf bank_mask:0xf
	v_mov_b32_dpp v100, v42 row_ror:15 row_mask:0xf bank_mask:0xf
	v_mov_b32_dpp v99, v109 row_ror:1 row_mask:0xf bank_mask:0xf
	v_mov_b32_dpp v101, v43 row_ror:15 row_mask:0xf bank_mask:0xf
	v_mov_b32_dpp v94, v106 row_ror:1 row_mask:0xf bank_mask:0xf
	v_mov_b32_dpp v96, v44 row_ror:15 row_mask:0xf bank_mask:0xf
	v_mov_b32_dpp v95, v107 row_ror:1 row_mask:0xf bank_mask:0xf
	v_mov_b32_dpp v97, v45 row_ror:15 row_mask:0xf bank_mask:0xf
	v_mov_b32_dpp v82, v104 row_ror:1 row_mask:0xf bank_mask:0xf
	v_mov_b32_dpp v84, v38 row_ror:15 row_mask:0xf bank_mask:0xf
	v_mov_b32_dpp v83, v105 row_ror:1 row_mask:0xf bank_mask:0xf
	v_mov_b32_dpp v85, v39 row_ror:15 row_mask:0xf bank_mask:0xf
	v_mov_b32_dpp v78, v102 row_ror:1 row_mask:0xf bank_mask:0xf
	v_mov_b32_dpp v80, v40 row_ror:15 row_mask:0xf bank_mask:0xf
	v_mov_b32_dpp v79, v103 row_ror:1 row_mask:0xf bank_mask:0xf
	v_mov_b32_dpp v81, v41 row_ror:15 row_mask:0xf bank_mask:0xf
	v_cmp_gt_i32_e32 vcc, s26, v110
	v_mov_b32_dpp v98, v92 row_shr:1 row_mask:0xf bank_mask:0xf
	v_mov_b32_dpp v100, v92 row_shl:1 row_mask:0xf bank_mask:0xf
	v_mov_b32_dpp v99, v93 row_shr:1 row_mask:0xf bank_mask:0xf
	v_mov_b32_dpp v101, v93 row_shl:1 row_mask:0xf bank_mask:0xf
	v_mov_b32_dpp v94, v90 row_shr:1 row_mask:0xf bank_mask:0xf
	v_mov_b32_dpp v96, v90 row_shl:1 row_mask:0xf bank_mask:0xf
	v_mov_b32_dpp v95, v91 row_shr:1 row_mask:0xf bank_mask:0xf
	v_mov_b32_dpp v97, v91 row_shl:1 row_mask:0xf bank_mask:0xf
	v_mov_b32_dpp v82, v88 row_shr:1 row_mask:0xf bank_mask:0xf
	v_mov_b32_dpp v84, v88 row_shl:1 row_mask:0xf bank_mask:0xf
	v_mov_b32_dpp v83, v89 row_shr:1 row_mask:0xf bank_mask:0xf
	v_mov_b32_dpp v85, v89 row_shl:1 row_mask:0xf bank_mask:0xf
	v_mov_b32_dpp v78, v86 row_shr:1 row_mask:0xf bank_mask:0xf
	v_mov_b32_dpp v80, v86 row_shl:1 row_mask:0xf bank_mask:0xf
	v_mov_b32_dpp v79, v87 row_shr:1 row_mask:0xf bank_mask:0xf
	v_mov_b32_dpp v81, v87 row_shl:1 row_mask:0xf bank_mask:0xf
	s_and_b64 s[0:1], s[36:37], vcc
	s_and_saveexec_b64 s[46:47], s[0:1]
	s_cbranch_execz .LBB0_673
	v_and_b32_e32 v105, s34, v110
	v_cmp_eq_u32_e32 vcc, 0, v105
	v_mov_b32_e32 v178, v179
	v_mov_b32_e32 v102, v179
	v_cndmask_b32_e64 v104, 1.0, 0, vcc
	v_cmp_eq_u32_e32 vcc, s34, v105
	v_mov_b32_e32 v103, v179
	v_pk_mul_f32 v[36:37], v[36:37], v[102:103]
	v_cndmask_b32_e64 v106, 1.0, 0, vcc
	v_pk_mul_f32 v[108:109], v[106:107], v[54:55] op_sel_hi:[0,1]
	v_pk_fma_f32 v[100:101], v[108:109], v[100:101], v[58:59]
	v_pk_mul_f32 v[102:103], v[32:33], v[102:103]
	v_pk_mul_f32 v[32:33], v[30:31], v[178:179]
	v_pk_mul_f32 v[30:31], v[104:105], v[50:51] op_sel_hi:[0,1]
	v_pk_fma_f32 v[100:101], v[92:93], v[46:47], v[100:101]
	s_mov_b32 s0, 0xc0135761
	v_pk_fma_f32 v[30:31], v[30:31], v[98:99], v[100:101]
	v_mov_b64_e32 v[100:101], s[0:1]
	v_pk_mul_f32 v[98:99], v[30:31], v[30:31]
	s_mov_b32 s0, 0x3dd2d3e8
	v_pk_fma_f32 v[98:99], v[98:99], s[0:1], v[100:101] op_sel_hi:[1,0,0] neg_lo:[1,0,0] neg_hi:[1,0,0]
	v_pk_mul_f32 v[34:35], v[34:35], v[178:179]
	v_pk_mul_f32 v[98:99], v[30:31], v[98:99]
	s_nop 0
	v_exp_f32_e32 v98, v98
	v_exp_f32_e32 v99, v99
	s_nop 0
	v_pk_add_f32 v[98:99], v[98:99], 1.0 op_sel_hi:[1,0]
	s_nop 0
	v_rcp_f32_e32 v98, v98
	v_rcp_f32_e32 v99, v99
	s_nop 0
	v_pk_mul_f32 v[30:31], v[30:31], v[98:99]
	v_pk_mul_f32 v[98:99], v[106:107], v[56:57] op_sel_hi:[0,1]
	v_pk_fma_f32 v[96:97], v[98:99], v[96:97], v[60:61]
	v_pk_mul_f32 v[30:31], v[34:35], v[30:31]
	v_pk_mul_f32 v[34:35], v[104:105], v[52:53] op_sel_hi:[0,1]
	v_pk_fma_f32 v[96:97], v[90:91], v[48:49], v[96:97]
	v_cvt_pk_bf16_f32 v30, v30, v31
	v_pk_fma_f32 v[34:35], v[34:35], v[94:95], v[96:97]
	s_nop 0
	v_pk_mul_f32 v[94:95], v[34:35], v[34:35]
	s_nop 0
	v_pk_fma_f32 v[94:95], v[94:95], s[0:1], v[100:101] op_sel_hi:[1,0,0] neg_lo:[1,0,0] neg_hi:[1,0,0]
	s_nop 0
	v_pk_mul_f32 v[94:95], v[34:35], v[94:95]
	s_nop 0
	v_exp_f32_e32 v94, v94
	v_exp_f32_e32 v95, v95
	s_nop 0
	v_pk_add_f32 v[94:95], v[94:95], 1.0 op_sel_hi:[1,0]
	s_nop 0
	v_rcp_f32_e32 v94, v94
	v_rcp_f32_e32 v95, v95
	s_nop 0
	v_pk_mul_f32 v[34:35], v[34:35], v[94:95]
	s_nop 0
	v_pk_mul_f32 v[34:35], v[36:37], v[34:35]
	v_pk_mul_f32 v[36:37], v[106:107], v[70:71] op_sel_hi:[0,1]
	v_pk_fma_f32 v[36:37], v[36:37], v[84:85], v[66:67]
	v_cvt_pk_bf16_f32 v31, v34, v35
	v_pk_mul_f32 v[34:35], v[104:105], v[74:75] op_sel_hi:[0,1]
	v_pk_fma_f32 v[36:37], v[88:89], v[62:63], v[36:37]
	s_nop 0
	v_pk_fma_f32 v[34:35], v[34:35], v[82:83], v[36:37]
	s_nop 0
	v_pk_mul_f32 v[36:37], v[34:35], v[34:35]
	s_nop 0
	v_pk_fma_f32 v[36:37], v[36:37], s[0:1], v[100:101] op_sel_hi:[1,0,0] neg_lo:[1,0,0] neg_hi:[1,0,0]
	s_nop 0
	v_pk_mul_f32 v[36:37], v[34:35], v[36:37]
	s_nop 0
	v_exp_f32_e32 v36, v36
	v_exp_f32_e32 v37, v37
	s_nop 0
	v_pk_add_f32 v[36:37], v[36:37], 1.0 op_sel_hi:[1,0]
	s_nop 0
	v_rcp_f32_e32 v36, v36
	v_rcp_f32_e32 v37, v37
	s_nop 0
	v_pk_mul_f32 v[34:35], v[34:35], v[36:37]
	v_pk_mul_f32 v[36:37], v[106:107], v[72:73] op_sel_hi:[0,1]
	v_pk_fma_f32 v[36:37], v[36:37], v[80:81], v[68:69]
	v_pk_mul_f32 v[32:33], v[32:33], v[34:35]
	v_pk_mul_f32 v[34:35], v[104:105], v[76:77] op_sel_hi:[0,1]
	v_pk_fma_f32 v[36:37], v[86:87], v[64:65], v[36:37]
	v_cvt_pk_bf16_f32 v32, v32, v33
	v_pk_fma_f32 v[34:35], v[34:35], v[78:79], v[36:37]
	s_nop 0
	v_pk_mul_f32 v[36:37], v[34:35], v[34:35]
	s_nop 0
	v_pk_fma_f32 v[36:37], v[36:37], s[0:1], v[100:101] op_sel_hi:[1,0,0] neg_lo:[1,0,0] neg_hi:[1,0,0]
	s_nop 0
	v_pk_mul_f32 v[36:37], v[34:35], v[36:37]
	s_nop 0
	v_exp_f32_e32 v36, v36
	v_exp_f32_e32 v37, v37
	s_nop 0
	v_pk_add_f32 v[36:37], v[36:37], 1.0 op_sel_hi:[1,0]
	s_nop 0
	v_rcp_f32_e32 v36, v36
	v_rcp_f32_e32 v37, v37
	s_nop 0
	v_pk_mul_f32 v[34:35], v[34:35], v[36:37]
	s_nop 0
	v_pk_mul_f32 v[34:35], v[102:103], v[34:35]
	s_nop 0
	v_cvt_pk_bf16_f32 v33, v34, v35
	v_mov_b64_e32 v[34:35], s[18:19]
	v_mad_i64_i32 v[34:35], s[0:1], v110, s27, v[34:35]
	v_lshl_add_u64 v[34:35], v[176:177], 1, v[34:35]
	global_store_dwordx4 v[34:35], v[30:33], off
;     __device__ __forceinline__ void operator()(const f32x4 (&acc_)[2][2][4][2], const Unit& u, int wr, int wc, int fr, int fq) const {
;     ...
;                     const f32x4 w0 = *(const PG8_LAS f32x4*)(wl + jj + 4 * n), w1 = *(const PG8_LAS f32x4*)(wl + 128 + jj + 4 * n), w2 = *(const PG8_LAS f32x4*)(wl + 256 + jj + 4 * n), bb = *(const PG8_LAS f32x4*)(wl + 384 + jj + 4 * n);
;                     f32x4 bp = {0.f, 0.f, 0.f, 0.f}, bn = {0.f, 0.f, 0.f, 0.f};
;                     if (m == 0 && sp >= 0) bp = *(const PG8_LAS f32x4*)(xg + sp * 128 + jj + 4 * n) * xg[1536 + ai * HALF + wr * 64 - 1];
;                     if (m == 3 && sn >= 0) bn = *(const PG8_LAS f32x4*)(xg + sn * 128 + jj + 4 * n) * xg[1536 + ai * HALF + wr * 64 + 64];
; #pragma unroll
;                     for (int eh = 0; eh < 2; ++eh) { v2f gv, p, q, up;
; #pragma unroll
;                         for (int k = 0; k < 2; ++k) { const int e = 2 * eh + k; const float g0 = acc[ai][0][m][n][e];
;                             const float pa = m > 0 ? dpp_ror1(acc[ai][0][m > 0 ? m - 1 : 0][n][e]) : bp[e];
;                             const float qa = m < 3 ? dpp_ror15(acc[ai][0][m < 3 ? m + 1 : 3][n][e]) : bn[e];
;                             gv[k] = g0; up[k] = acc[ai][1][m][n][e];
;                             p[k] = __builtin_bit_cast(float, __builtin_amdgcn_update_dpp(__builtin_bit_cast(int, pa), __builtin_bit_cast(int, g0), 0x111, 0xf, 0xf, false));
;                             q[k] = __builtin_bit_cast(float, __builtin_amdgcn_update_dpp(__builtin_bit_cast(int, qa), __builtin_bit_cast(int, g0), 0x101, 0xf, 0xf, false)); }
;                         const v2f a0 = (v2f){w0[2 * eh], w0[2 * eh + 1]} * mp, a1 = (v2f){w1[2 * eh], w1[2 * eh + 1]}, a2 = (v2f){w2[2 * eh], w2[2 * eh + 1]} * mn, ab = (v2f){bb[2 * eh], bb[2 * eh + 1]};
;                         const v2f x = a0 * p + (a1 * gv + (a2 * q + ab));
;                         const v2f arg = x * ((x * x) * (-0.10294324f) + (-2.3022082f));
;                         v2f ex; ex[0] = __builtin_amdgcn_exp2f(arg[0]); ex[1] = __builtin_amdgcn_exp2f(arg[1]);
;                         const v2f dn = ex + 1.0f; v2f rc; rc[0] = __builtin_amdgcn_rcpf(dn[0]); rc[1] = __builtin_amdgcn_rcpf(dn[1]);
;                         const v2f y = (x * rc) * up;
;                         ov[2 * n + eh] = cvt_pk_bf16(y[0], y[1]); }
;                 }
.LBB0_673:
	s_or_b64 exec, exec, s[46:47]
	s_nop 0
	v_mov_b32_e32 v30, v175
	v_pk_mul_f32 v[28:29], v[28:29], v[30:31] op_sel_hi:[1,0]
	v_pk_mul_f32 v[26:27], v[26:27], v[30:31] op_sel_hi:[1,0]
	v_pk_mul_f32 v[24:25], v[24:25], v[30:31] op_sel_hi:[1,0]
	v_pk_mul_f32 v[22:23], v[22:23], v[30:31] op_sel_hi:[1,0]
	v_add_u32_e32 v94, s33, v226
	v_mov_b32_dpp v82, v92 row_ror:1 row_mask:0xf bank_mask:0xf
	v_mov_b32_dpp v84, v26 row_ror:15 row_mask:0xf bank_mask:0xf
	v_mov_b32_dpp v83, v93 row_ror:1 row_mask:0xf bank_mask:0xf
	v_mov_b32_dpp v85, v27 row_ror:15 row_mask:0xf bank_mask:0xf
	v_mov_b32_dpp v78, v90 row_ror:1 row_mask:0xf bank_mask:0xf
	v_mov_b32_dpp v80, v28 row_ror:15 row_mask:0xf bank_mask:0xf
	v_mov_b32_dpp v79, v91 row_ror:1 row_mask:0xf bank_mask:0xf
	v_mov_b32_dpp v81, v29 row_ror:15 row_mask:0xf bank_mask:0xf
	v_mov_b32_dpp v34, v88 row_ror:1 row_mask:0xf bank_mask:0xf
	v_mov_b32_dpp v36, v22 row_ror:15 row_mask:0xf bank_mask:0xf
	v_mov_b32_dpp v35, v89 row_ror:1 row_mask:0xf bank_mask:0xf
	v_mov_b32_dpp v37, v23 row_ror:15 row_mask:0xf bank_mask:0xf
	v_mov_b32_dpp v30, v86 row_ror:1 row_mask:0xf bank_mask:0xf
	v_mov_b32_dpp v32, v24 row_ror:15 row_mask:0xf bank_mask:0xf
	v_mov_b32_dpp v31, v87 row_ror:1 row_mask:0xf bank_mask:0xf
	v_mov_b32_dpp v33, v25 row_ror:15 row_mask:0xf bank_mask:0xf
	v_cmp_gt_i32_e32 vcc, s26, v94
	v_mov_b32_dpp v82, v42 row_shr:1 row_mask:0xf bank_mask:0xf
	v_mov_b32_dpp v84, v42 row_shl:1 row_mask:0xf bank_mask:0xf
	v_mov_b32_dpp v83, v43 row_shr:1 row_mask:0xf bank_mask:0xf
	v_mov_b32_dpp v85, v43 row_shl:1 row_mask:0xf bank_mask:0xf
	v_mov_b32_dpp v78, v44 row_shr:1 row_mask:0xf bank_mask:0xf
	v_mov_b32_dpp v80, v44 row_shl:1 row_mask:0xf bank_mask:0xf
	v_mov_b32_dpp v79, v45 row_shr:1 row_mask:0xf bank_mask:0xf
	v_mov_b32_dpp v81, v45 row_shl:1 row_mask:0xf bank_mask:0xf
	v_mov_b32_dpp v34, v38 row_shr:1 row_mask:0xf bank_mask:0xf
	v_mov_b32_dpp v36, v38 row_shl:1 row_mask:0xf bank_mask:0xf
	v_mov_b32_dpp v35, v39 row_shr:1 row_mask:0xf bank_mask:0xf
	v_mov_b32_dpp v37, v39 row_shl:1 row_mask:0xf bank_mask:0xf
	v_mov_b32_dpp v30, v40 row_shr:1 row_mask:0xf bank_mask:0xf
	v_mov_b32_dpp v32, v40 row_shl:1 row_mask:0xf bank_mask:0xf
	v_mov_b32_dpp v31, v41 row_shr:1 row_mask:0xf bank_mask:0xf
	v_mov_b32_dpp v33, v41 row_shl:1 row_mask:0xf bank_mask:0xf
	s_and_b64 s[0:1], s[38:39], vcc
	s_and_saveexec_b64 s[46:47], s[0:1]
	s_cbranch_execz .LBB0_675
	v_mov_b32_e32 v86, v174
	v_mov_b32_e32 v87, v174
	v_mov_b32_e32 v88, v174
	v_mov_b32_e32 v89, v174
	v_pk_mul_f32 v[20:21], v[20:21], v[88:89]
	v_pk_mul_f32 v[18:19], v[18:19], v[86:87]
	v_pk_mul_f32 v[88:89], v[16:17], v[88:89]
	v_pk_mul_f32 v[16:17], v[14:15], v[86:87]
	v_and_b32_e32 v87, s34, v94
	v_cmp_eq_u32_e32 vcc, 0, v87
	s_mov_b32 s0, 0xc0135761
	s_nop 0
	v_cndmask_b32_e64 v86, 1.0, 0, vcc
	v_cmp_eq_u32_e32 vcc, s34, v87
	v_pk_mul_f32 v[14:15], v[86:87], v[50:51] op_sel_hi:[0,1]
	s_nop 0
	v_cndmask_b32_e64 v90, 1.0, 0, vcc
	v_pk_mul_f32 v[92:93], v[90:91], v[54:55] op_sel_hi:[0,1]
	v_pk_fma_f32 v[84:85], v[92:93], v[84:85], v[58:59]
	s_nop 0
	v_pk_fma_f32 v[84:85], v[42:43], v[46:47], v[84:85]
	s_nop 0
	v_pk_fma_f32 v[14:15], v[14:15], v[82:83], v[84:85]
	v_mov_b64_e32 v[84:85], s[0:1]
	v_pk_mul_f32 v[82:83], v[14:15], v[14:15]
	s_mov_b32 s0, 0x3dd2d3e8
	v_pk_fma_f32 v[82:83], v[82:83], s[0:1], v[84:85] op_sel_hi:[1,0,0] neg_lo:[1,0,0] neg_hi:[1,0,0]
	s_nop 0
	v_pk_mul_f32 v[82:83], v[14:15], v[82:83]
	s_nop 0
	v_exp_f32_e32 v82, v82
	v_exp_f32_e32 v83, v83
	s_nop 0
	v_pk_add_f32 v[82:83], v[82:83], 1.0 op_sel_hi:[1,0]
	s_nop 0
	v_rcp_f32_e32 v82, v82
	v_rcp_f32_e32 v83, v83
	s_nop 0
	v_pk_mul_f32 v[14:15], v[14:15], v[82:83]
	v_pk_mul_f32 v[82:83], v[90:91], v[56:57] op_sel_hi:[0,1]
	v_pk_fma_f32 v[80:81], v[82:83], v[80:81], v[60:61]
	v_pk_mul_f32 v[14:15], v[18:19], v[14:15]
	v_pk_mul_f32 v[18:19], v[86:87], v[52:53] op_sel_hi:[0,1]
	v_pk_fma_f32 v[80:81], v[44:45], v[48:49], v[80:81]
	v_cvt_pk_bf16_f32 v14, v14, v15
	v_pk_fma_f32 v[18:19], v[18:19], v[78:79], v[80:81]
	s_nop 0
	v_pk_mul_f32 v[78:79], v[18:19], v[18:19]
	s_nop 0
	v_pk_fma_f32 v[78:79], v[78:79], s[0:1], v[84:85] op_sel_hi:[1,0,0] neg_lo:[1,0,0] neg_hi:[1,0,0]
	s_nop 0
	v_pk_mul_f32 v[78:79], v[18:19], v[78:79]
	s_nop 0
	v_exp_f32_e32 v78, v78
	v_exp_f32_e32 v79, v79
	s_nop 0
	v_pk_add_f32 v[78:79], v[78:79], 1.0 op_sel_hi:[1,0]
	s_nop 0
	v_rcp_f32_e32 v78, v78
	v_rcp_f32_e32 v79, v79
	s_nop 0
	v_pk_mul_f32 v[18:19], v[18:19], v[78:79]
	s_nop 0
	v_pk_mul_f32 v[18:19], v[20:21], v[18:19]
	v_pk_mul_f32 v[20:21], v[90:91], v[70:71] op_sel_hi:[0,1]
	v_pk_fma_f32 v[20:21], v[20:21], v[36:37], v[66:67]
	v_cvt_pk_bf16_f32 v15, v18, v19
	v_pk_mul_f32 v[18:19], v[86:87], v[74:75] op_sel_hi:[0,1]
	v_pk_fma_f32 v[20:21], v[38:39], v[62:63], v[20:21]
	s_nop 0
	v_pk_fma_f32 v[18:19], v[18:19], v[34:35], v[20:21]
	s_nop 0
	v_pk_mul_f32 v[20:21], v[18:19], v[18:19]
	s_nop 0
	v_pk_fma_f32 v[20:21], v[20:21], s[0:1], v[84:85] op_sel_hi:[1,0,0] neg_lo:[1,0,0] neg_hi:[1,0,0]
	s_nop 0
	v_pk_mul_f32 v[20:21], v[18:19], v[20:21]
	s_nop 0
	v_exp_f32_e32 v20, v20
	v_exp_f32_e32 v21, v21
	s_nop 0
	v_pk_add_f32 v[20:21], v[20:21], 1.0 op_sel_hi:[1,0]
	s_nop 0
	v_rcp_f32_e32 v20, v20
	v_rcp_f32_e32 v21, v21
	s_nop 0
	v_pk_mul_f32 v[18:19], v[18:19], v[20:21]
	v_pk_mul_f32 v[20:21], v[90:91], v[72:73] op_sel_hi:[0,1]
	v_pk_fma_f32 v[20:21], v[20:21], v[32:33], v[68:69]
	v_pk_mul_f32 v[16:17], v[16:17], v[18:19]
	v_pk_mul_f32 v[18:19], v[86:87], v[76:77] op_sel_hi:[0,1]
	v_pk_fma_f32 v[20:21], v[40:41], v[64:65], v[20:21]
	v_cvt_pk_bf16_f32 v16, v16, v17
	v_pk_fma_f32 v[18:19], v[18:19], v[30:31], v[20:21]
	s_nop 0
	v_pk_mul_f32 v[20:21], v[18:19], v[18:19]
	s_nop 0
	v_pk_fma_f32 v[20:21], v[20:21], s[0:1], v[84:85] op_sel_hi:[1,0,0] neg_lo:[1,0,0] neg_hi:[1,0,0]
	s_nop 0
	v_pk_mul_f32 v[20:21], v[18:19], v[20:21]
	s_nop 0
	v_exp_f32_e32 v20, v20
	v_exp_f32_e32 v21, v21
	s_nop 0
	v_pk_add_f32 v[20:21], v[20:21], 1.0 op_sel_hi:[1,0]
	s_nop 0
	v_rcp_f32_e32 v20, v20
	v_rcp_f32_e32 v21, v21
	s_nop 0
	v_pk_mul_f32 v[18:19], v[18:19], v[20:21]
	s_nop 0
	v_pk_mul_f32 v[18:19], v[88:89], v[18:19]
	s_nop 0
	v_cvt_pk_bf16_f32 v17, v18, v19
	v_mov_b64_e32 v[18:19], s[18:19]
	v_mad_i64_i32 v[18:19], s[0:1], v94, s27, v[18:19]
	v_lshl_add_u64 v[18:19], v[176:177], 1, v[18:19]
	global_store_dwordx4 v[18:19], v[14:17], off

;     __device__ __forceinline__ void operator()(const f32x4 (&acc_)[2][2][4][2], const Unit& u, int wr, int wc, int fr, int fq) const {
;     ...
;                     const f32x4 w0 = *(const PG8_LAS f32x4*)(wl + jj + 4 * n), w1 = *(const PG8_LAS f32x4*)(wl + 128 + jj + 4 * n), w2 = *(const PG8_LAS f32x4*)(wl + 256 + jj + 4 * n), bb = *(const PG8_LAS f32x4*)(wl + 384 + jj + 4 * n);
;                     f32x4 bp = {0.f, 0.f, 0.f, 0.f}, bn = {0.f, 0.f, 0.f, 0.f};
;                     if (m == 0 && sp >= 0) bp = *(const PG8_LAS f32x4*)(xg + sp * 128 + jj + 4 * n) * xg[1536 + ai * HALF + wr * 64 - 1];
;                     if (m == 3 && sn >= 0) bn = *(const PG8_LAS f32x4*)(xg + sn * 128 + jj + 4 * n) * xg[1536 + ai * HALF + wr * 64 + 64];
; #pragma unroll
;                     for (int eh = 0; eh < 2; ++eh) { v2f gv, p, q, up;
; #pragma unroll
;                         for (int k = 0; k < 2; ++k) { const int e = 2 * eh + k; const float g0 = acc[ai][0][m][n][e];
;                             const float pa = m > 0 ? dpp_ror1(acc[ai][0][m > 0 ? m - 1 : 0][n][e]) : bp[e];
;                             const float qa = m < 3 ? dpp_ror15(acc[ai][0][m < 3 ? m + 1 : 3][n][e]) : bn[e];
;                             gv[k] = g0; up[k] = acc[ai][1][m][n][e];
;                             p[k] = __builtin_bit_cast(float, __builtin_amdgcn_update_dpp(__builtin_bit_cast(int, pa), __builtin_bit_cast(int, g0), 0x111, 0xf, 0xf, false));
;                             q[k] = __builtin_bit_cast(float, __builtin_amdgcn_update_dpp(__builtin_bit_cast(int, qa), __builtin_bit_cast(int, g0), 0x101, 0xf, 0xf, false)); }
;                         const v2f a0 = (v2f){w0[2 * eh], w0[2 * eh + 1]} * mp, a1 = (v2f){w1[2 * eh], w1[2 * eh + 1]}, a2 = (v2f){w2[2 * eh], w2[2 * eh + 1]} * mn, ab = (v2f){bb[2 * eh], bb[2 * eh + 1]};
;                         const v2f x = a0 * p + (a1 * gv + (a2 * q + ab));
;                         const v2f arg = x * ((x * x) * (-0.10294324f) + (-2.3022082f));
;                         v2f ex; ex[0] = __builtin_amdgcn_exp2f(arg[0]); ex[1] = __builtin_amdgcn_exp2f(arg[1]);
;                         const v2f dn = ex + 1.0f; v2f rc; rc[0] = __builtin_amdgcn_rcpf(dn[0]); rc[1] = __builtin_amdgcn_rcpf(dn[1]);
;                         const v2f y = (x * rc) * up;
;                         ov[2 * n + eh] = cvt_pk_bf16(y[0], y[1]); }
;                 }
.LBB0_677:
	v_mov_b32_dpp v36, v42 row_ror:1 row_mask:0xf bank_mask:0xf
	v_mov_b32_dpp v37, v43 row_ror:1 row_mask:0xf bank_mask:0xf
	v_mov_b32_dpp v30, v44 row_ror:1 row_mask:0xf bank_mask:0xf
	v_mov_b32_dpp v31, v45 row_ror:1 row_mask:0xf bank_mask:0xf
	v_mov_b32_dpp v36, v26 row_shr:1 row_mask:0xf bank_mask:0xf
	v_mov_b32_dpp v32, v26 row_shl:1 row_mask:0xf bank_mask:0xf
	v_mov_b32_dpp v37, v27 row_shr:1 row_mask:0xf bank_mask:0xf
	v_mov_b32_dpp v33, v27 row_shl:1 row_mask:0xf bank_mask:0xf
	v_mov_b32_dpp v30, v28 row_shr:1 row_mask:0xf bank_mask:0xf
	v_mov_b32_dpp v18, v28 row_shl:1 row_mask:0xf bank_mask:0xf
	v_mov_b32_dpp v31, v29 row_shr:1 row_mask:0xf bank_mask:0xf
	v_mov_b32_dpp v19, v29 row_shl:1 row_mask:0xf bank_mask:0xf
	s_and_b64 vcc, exec, s[46:47]
	v_mov_b32_e32 v15, 0
	v_mov_b32_e32 v16, 0
	v_mov_b32_e32 v17, 0
	s_cbranch_vccnz .LBB0_679
	v_mov_b32_e32 v20, s79
	ds_read_b128 v[14:17], v242 offset:16
	ds_read_b32 v20, v20 offset:6912
	s_waitcnt lgkmcnt(0)
	v_pk_mul_f32 v[16:17], v[16:17], v[20:21] op_sel_hi:[1,0]
	v_pk_mul_f32 v[14:15], v[14:15], v[20:21] op_sel_hi:[1,0]
.LBB0_679:
	v_add_u32_e32 v42, s33, v227
	v_mov_b32_dpp v34, v38 row_ror:1 row_mask:0xf bank_mask:0xf
	v_mov_b32_dpp v35, v39 row_ror:1 row_mask:0xf bank_mask:0xf
	v_mov_b32_dpp v20, v40 row_ror:1 row_mask:0xf bank_mask:0xf
	v_mov_b32_dpp v21, v41 row_ror:1 row_mask:0xf bank_mask:0xf
	v_cmp_gt_i32_e32 vcc, s26, v42
	v_mov_b32_dpp v34, v22 row_shr:1 row_mask:0xf bank_mask:0xf
	v_mov_b32_dpp v14, v22 row_shl:1 row_mask:0xf bank_mask:0xf
	v_mov_b32_dpp v35, v23 row_shr:1 row_mask:0xf bank_mask:0xf
	v_mov_b32_dpp v15, v23 row_shl:1 row_mask:0xf bank_mask:0xf
	v_mov_b32_dpp v20, v24 row_shr:1 row_mask:0xf bank_mask:0xf
	v_mov_b32_dpp v16, v24 row_shl:1 row_mask:0xf bank_mask:0xf
	v_mov_b32_dpp v21, v25 row_shr:1 row_mask:0xf bank_mask:0xf
	v_mov_b32_dpp v17, v25 row_shl:1 row_mask:0xf bank_mask:0xf
	s_and_b64 s[0:1], s[40:41], vcc
	s_and_saveexec_b64 s[46:47], s[0:1]
	s_cbranch_execz .LBB0_681
	v_and_b32_e32 v39, s34, v42
	v_cmp_eq_u32_e32 vcc, 0, v39
	s_mov_b32 s0, 0xc0135761
	v_mov_b32_e32 v44, v175
	v_cndmask_b32_e64 v38, 1.0, 0, vcc
	v_cmp_eq_u32_e32 vcc, s34, v39
	v_pk_mul_f32 v[50:51], v[38:39], v[50:51] op_sel_hi:[0,1]
	v_mov_b32_e32 v45, v175
	v_cndmask_b32_e64 v40, 1.0, 0, vcc
	v_pk_mul_f32 v[54:55], v[40:41], v[54:55] op_sel_hi:[0,1]
	v_pk_fma_f32 v[32:33], v[54:55], v[32:33], v[58:59]
	v_mov_b32_e32 v174, v175
	v_pk_fma_f32 v[26:27], v[46:47], v[26:27], v[32:33]
	v_pk_mul_f32 v[46:47], v[38:39], v[52:53] op_sel_hi:[0,1]
	v_pk_fma_f32 v[26:27], v[50:51], v[36:37], v[26:27]
	v_pk_mul_f32 v[50:51], v[40:41], v[56:57] op_sel_hi:[0,1]
	v_pk_fma_f32 v[18:19], v[50:51], v[18:19], v[60:61]
	v_mov_b64_e32 v[36:37], s[0:1]
	v_pk_fma_f32 v[18:19], v[48:49], v[28:29], v[18:19]
	s_mov_b32 s0, 0x3dd2d3e8
	v_pk_fma_f32 v[18:19], v[46:47], v[30:31], v[18:19]
	v_pk_mul_f32 v[32:33], v[26:27], v[26:27]
	v_pk_mul_f32 v[28:29], v[18:19], v[18:19]
	v_pk_fma_f32 v[32:33], v[32:33], s[0:1], v[36:37] op_sel_hi:[1,0,0] neg_lo:[1,0,0] neg_hi:[1,0,0]
	v_pk_fma_f32 v[28:29], v[28:29], s[0:1], v[36:37] op_sel_hi:[1,0,0] neg_lo:[1,0,0] neg_hi:[1,0,0]
	v_pk_mul_f32 v[32:33], v[26:27], v[32:33]
	v_pk_mul_f32 v[28:29], v[18:19], v[28:29]
	v_exp_f32_e32 v32, v32
	v_exp_f32_e32 v28, v28
	v_exp_f32_e32 v29, v29
	v_exp_f32_e32 v33, v33
	v_pk_mul_f32 v[12:13], v[12:13], v[44:45]
	v_pk_mul_f32 v[10:11], v[10:11], v[174:175]
	v_pk_add_f32 v[28:29], v[28:29], 1.0 op_sel_hi:[1,0]
	v_pk_add_f32 v[30:31], v[32:33], 1.0 op_sel_hi:[1,0]
	v_rcp_f32_e32 v28, v28
	v_rcp_f32_e32 v29, v29
	v_rcp_f32_e32 v30, v30
	v_rcp_f32_e32 v31, v31
	v_pk_mul_f32 v[6:7], v[6:7], v[174:175]
	v_pk_mul_f32 v[18:19], v[18:19], v[28:29]
	v_pk_mul_f32 v[8:9], v[8:9], v[44:45]
	v_pk_mul_f32 v[26:27], v[26:27], v[30:31]
	v_pk_mul_f32 v[12:13], v[12:13], v[18:19]
	v_pk_mul_f32 v[18:19], v[40:41], v[70:71] op_sel_hi:[0,1]
	v_pk_mul_f32 v[10:11], v[10:11], v[26:27]
	v_pk_fma_f32 v[14:15], v[18:19], v[14:15], v[66:67]
	v_cvt_pk_bf16_f32 v10, v10, v11
	v_cvt_pk_bf16_f32 v11, v12, v13
	v_pk_mul_f32 v[12:13], v[38:39], v[74:75] op_sel_hi:[0,1]
	v_pk_fma_f32 v[14:15], v[22:23], v[62:63], v[14:15]
	v_pk_mul_f32 v[22:23], v[40:41], v[72:73] op_sel_hi:[0,1]
	v_pk_fma_f32 v[12:13], v[12:13], v[34:35], v[14:15]
	v_pk_fma_f32 v[16:17], v[22:23], v[16:17], v[68:69]
	v_pk_mul_f32 v[14:15], v[12:13], v[12:13]
	v_pk_mul_f32 v[18:19], v[38:39], v[76:77] op_sel_hi:[0,1]
	v_pk_fma_f32 v[16:17], v[24:25], v[64:65], v[16:17]
	v_pk_fma_f32 v[14:15], v[14:15], s[0:1], v[36:37] op_sel_hi:[1,0,0] neg_lo:[1,0,0] neg_hi:[1,0,0]
	v_pk_fma_f32 v[16:17], v[18:19], v[20:21], v[16:17]
	v_pk_mul_f32 v[14:15], v[12:13], v[14:15]
	v_pk_mul_f32 v[18:19], v[16:17], v[16:17]
	v_exp_f32_e32 v14, v14
	v_exp_f32_e32 v15, v15
	v_pk_fma_f32 v[18:19], v[18:19], s[0:1], v[36:37] op_sel_hi:[1,0,0] neg_lo:[1,0,0] neg_hi:[1,0,0]
	v_pk_add_f32 v[14:15], v[14:15], 1.0 op_sel_hi:[1,0]
	v_pk_mul_f32 v[18:19], v[16:17], v[18:19]
	v_rcp_f32_e32 v14, v14
	v_exp_f32_e32 v18, v18
	v_exp_f32_e32 v19, v19
	v_rcp_f32_e32 v15, v15
	v_pk_add_f32 v[18:19], v[18:19], 1.0 op_sel_hi:[1,0]
	s_nop 0
	v_rcp_f32_e32 v18, v18
	v_rcp_f32_e32 v19, v19
	v_pk_mul_f32 v[12:13], v[12:13], v[14:15]
	s_nop 0
	v_pk_mul_f32 v[6:7], v[6:7], v[12:13]
	s_nop 0
	v_cvt_pk_bf16_f32 v12, v6, v7
	v_pk_mul_f32 v[6:7], v[16:17], v[18:19]
	s_nop 0
	v_pk_mul_f32 v[6:7], v[8:9], v[6:7]
	s_nop 0
	v_cvt_pk_bf16_f32 v13, v6, v7
	v_mov_b64_e32 v[6:7], s[18:19]
	v_mad_i64_i32 v[6:7], s[0:1], v42, s27, v[6:7]
	v_lshl_add_u64 v[6:7], v[176:177], 1, v[6:7]
	global_store_dwordx4 v[6:7], v[10:13], off
